# GU/Down K-loops: first two phases after an epilogue wait vmcnt(8+S) (S = epilogue stores) instead of vmcnt(8), so store acks are not waited for
# baseline (speedup 1.0000x reference)
.LBB0_1670:
	s_mov_b32 s101, 0
	s_cmp_lt_i32 s56, 10
	s_cselect_b64 s[8:9], -1, 0
	s_and_b64 s[6:7], s[8:9], s[6:7]
	s_andn2_b64 vcc, exec, s[6:7]
	s_cbranch_vccnz .LBB0_1687
	s_waitcnt vmcnt(0)
	v_mbcnt_hi_u32_b32 v132, -1, v254
	v_mov_b32_e32 v0, v132
	s_cmpk_gt_i32 s92, 0x5ff
	s_cbranch_scc1 .LBB0_1687
	s_lshl_b32 s3, s33, 10
	v_lshl_add_u32 v1, v0, 4, s3
	v_add_u32_e32 v2, 0x2000, v1
	v_ashrrev_i32_e32 v3, 31, v2
	v_lshrrev_b32_e32 v3, 22, v3
	v_add_u32_e32 v3, v2, v3
	v_ashrrev_i32_e32 v3, 10, v3
	v_mul_i32_i24_e32 v5, 0x400, v3
	v_sub_u32_e32 v2, v2, v5
	v_lshrrev_b32_e32 v5, 4, v2
	v_bitop3_b32 v2, v5, v2, 32 bitop3:0x6c
	v_ashrrev_i32_e32 v5, 31, v2
	v_lshrrev_b32_e32 v5, 26, v5
	v_add_u32_e32 v5, v2, v5
	v_ashrrev_i32_e32 v6, 6, v5
	v_and_b32_e32 v5, 0xffc0, v5
	v_sub_u32_e32 v2, v2, v5
	v_lshrrev_b16_e32 v5, 7, v2
	v_lshlrev_b32_e32 v4, 5, v3
	v_and_b32_e32 v5, 1, v5
	v_lshlrev_b32_e32 v3, 3, v3
	v_add_u16_e32 v2, v2, v5
	v_mov_b32_e32 v5, 1
	v_and_b32_e32 v3, -16, v3
	v_and_b32_e32 v4, 32, v4
	v_ashrrev_i16_sdwa v2, v5, sext(v2) dst_sel:DWORD dst_unused:UNUSED_PAD src0_sel:DWORD src1_sel:BYTE_0
	v_add_u32_e32 v3, v6, v3
	v_add_u32_sdwa v2, v4, sext(v2) dst_sel:DWORD dst_unused:UNUSED_PAD src0_sel:DWORD src1_sel:WORD_0
	v_and_b32_e32 v4, 3, v6
	s_mov_b32 s8, 0xfffffe0
	v_lshrrev_b32_e32 v6, 2, v3
	v_lshlrev_b32_e32 v7, 1, v3
	v_and_or_b32 v4, v3, s8, v4
	v_and_b32_e32 v6, 4, v6
	v_and_b32_e32 v7, 24, v7
	v_or3_b32 v4, v4, v6, v7
	v_ashrrev_i32_e32 v6, 31, v1
	v_lshrrev_b32_e32 v6, 22, v6
	v_add_u32_e32 v6, v1, v6
	v_ashrrev_i32_e32 v6, 10, v6
	v_mul_i32_i24_e32 v8, 0x400, v6
	v_sub_u32_e32 v1, v1, v8
	v_lshrrev_b32_e32 v8, 4, v1
	v_bitop3_b32 v1, v8, v1, 32 bitop3:0x6c
	v_ashrrev_i32_e32 v8, 31, v1
	v_lshrrev_b32_e32 v8, 26, v8
	v_add_u32_e32 v8, v1, v8
	v_ashrrev_i32_e32 v9, 6, v8
	v_and_b32_e32 v8, 0xc0, v8
	v_sub_u32_e32 v1, v1, v8
	v_ashrrev_i16_sdwa v1, v5, sext(v1) dst_sel:DWORD dst_unused:UNUSED_PAD src0_sel:DWORD src1_sel:BYTE_0
	v_lshlrev_b32_e32 v5, 3, v6
	v_and_b32_e32 v5, -16, v5
	v_lshlrev_b32_e32 v7, 5, v6
	v_add_u32_e32 v5, v9, v5
	v_and_b32_e32 v6, 3, v9
	v_and_or_b32 v6, v5, s8, v6
	s_mul_hi_i32 s8, s92, 0x2aaaaaab
	s_lshr_b32 s9, s8, 31
	s_ashr_i32 s8, s8, 4
	s_add_i32 s8, s8, s9
	s_mul_i32 s9, s8, 0x60
	s_sub_i32 s9, s92, s9
	s_bfe_i32 s10, s9, 0x80000
	s_mul_i32 s10, s10, 43
	s_bfe_u32 s11, s10, 0x1000f
	s_bfe_u32 s10, s10, 0x80008
	s_add_i32 s14, s10, s11
	s_load_dwordx2 s[16:17], s[0:1], 0xf0
	s_mul_i32 s11, s14, 6
	s_sub_i32 s9, s9, s11
	s_mul_i32 s10, s8, 6
	s_sext_i32_i8 s9, s9
	s_lshr_b32 s12, s90, 8
	s_add_i32 s28, s10, s9
	s_waitcnt lgkmcnt(0)
	s_add_u32 s19, s16, 0x5c358000
	s_addc_u32 s38, s17, 0
	s_ashr_i32 s29, s28, 31
	s_lshl_b64 s[10:11], s[28:29], 19
	s_add_u32 s30, s19, s10
	v_and_b32_e32 v7, 32, v7
	s_addc_u32 s31, s38, s11
	v_add_u32_sdwa v1, v7, sext(v1) dst_sel:DWORD dst_unused:UNUSED_PAD src0_sel:DWORD src1_sel:WORD_0
	v_lshrrev_b32_e32 v7, 2, v5
	v_lshlrev_b32_e32 v8, 1, v5
	s_add_u32 s39, s16, 0x33d8000
	v_lshlrev_b32_e32 v5, 11, v5
	v_and_b32_e32 v7, 4, v7
	v_and_b32_e32 v8, 24, v8
	s_addc_u32 s40, s17, 0
	s_ashr_i32 s9, s8, 31
	s_bfe_i64 s[10:11], s[14:15], 0x80000
	v_lshl_add_u32 v133, v1, 1, v5
	v_lshlrev_b32_e32 v1, 13, v1
	v_or3_b32 v6, v6, v7, v8
	s_lshl_b64 s[8:9], s[8:9], 23
	s_lshl_b64 s[10:11], s[10:11], 12
	v_and_b32_e32 v1, 0xffff0000, v1
	s_add_u32 s8, s39, s8
	v_lshl_add_u32 v135, v6, 4, v1
	v_lshlrev_b32_e32 v1, 13, v2
	s_addc_u32 s9, s40, s9
	v_and_b32_e32 v1, 0xffff0000, v1
	s_add_u32 s34, s8, s10
	v_lshlrev_b32_e32 v3, 11, v3
	v_lshl_add_u32 v136, v4, 4, v1
	s_addc_u32 s35, s9, s11
	v_lshl_add_u32 v134, v2, 1, v3
	v_mov_b32_e32 v1, v136
	v_mov_b32_e32 v2, v135
	s_add_i32 s41, s3, 0
	s_add_i32 m0, s41, 0x10000
	v_mov_b32_e32 v128, v135
	global_load_lds_dwordx4 v2, s[34:35]
	s_add_i32 m0, s41, 0x12000
	v_mov_b32_e32 v2, v136
	v_mov_b32_e32 v129, 0
	global_load_lds_dwordx4 v1, s[34:35]
	s_mov_b64 s[8:9], 0x800
	v_lshl_add_u64 v[4:5], s[34:35], 0, v[128:129]
	v_mov_b32_e32 v3, v129
	v_lshl_add_u64 v[4:5], v[4:5], 0, s[8:9]
	s_add_i32 m0, s41, 0x14000
	v_lshl_add_u64 v[2:3], s[34:35], 0, v[2:3]
	global_load_lds_dwordx4 v[4:5], off
	v_lshl_add_u64 v[2:3], v[2:3], 0, s[8:9]
	s_add_i32 m0, s41, 0x16000
	s_add_i32 s42, s41, 0x2000
	global_load_lds_dwordx4 v[2:3], off
	v_mov_b32_e32 v1, v133
	v_mov_b32_e32 v2, v134
	s_mov_b32 m0, s41
	s_add_u32 s10, s30, 0x40000
	s_addc_u32 s11, s31, 0
	global_load_lds_dwordx4 v1, s[30:31]
	s_mov_b32 m0, s42
	s_add_i32 s43, s41, 0x4000
	global_load_lds_dwordx4 v2, s[30:31]
	v_mov_b32_e32 v1, v134
	v_mov_b32_e32 v2, v133
	s_mov_b32 m0, s43
	s_add_i32 s44, s41, 0x6000
	s_cmp_eq_u32 s12, 1
	global_load_lds_dwordx4 v2, s[10:11]
	s_mov_b32 m0, s44
	s_nop 0
	global_load_lds_dwordx4 v1, s[10:11]
	s_cselect_b64 s[10:11], -1, 0
	s_cmp_lg_u32 s12, 1
	s_cbranch_scc1 .LBB0_1674
	s_barrier

.LBB0_1680:
	ds_read_b128 v[142:145], v138
	ds_read_b128 v[146:149], v138 offset:1024
	ds_read_b128 v[150:153], v138 offset:2048
	ds_read_b128 v[154:157], v138 offset:3072
	ds_read_b128 v[158:161], v139
	ds_read_b128 v[162:165], v139 offset:1024
	ds_read_b128 v[166:169], v139 offset:2048
	ds_read_b128 v[170:173], v139 offset:3072
	s_add_u32 s34, s30, 0xfffc0080
	s_addc_u32 s35, s31, -1
	s_cmp_eq_u32 s49, 12
	s_cselect_b32 s35, s23, s35
	s_cselect_b32 s34, s22, s34
	s_cselect_b32 s37, s25, s48
	s_cselect_b32 s36, s24, s21
	v_mov_b32_e32 v128, v133
	v_mov_b32_e32 v130, v134
	s_add_i32 m0, s41, 0xc000
	ds_read_b128 v[174:177], v140
	ds_read_b128 v[178:181], v140 offset:1024
	ds_read_b128 v[182:185], v140 offset:2048
	ds_read_b128 v[186:189], v140 offset:3072
	ds_read_b128 v[190:193], v140 offset:4096
	ds_read_b128 v[194:197], v140 offset:5120
	ds_read_b128 v[198:201], v140 offset:6144
	ds_read_b128 v[202:205], v140 offset:7168
	s_nop 0
	global_load_lds_dwordx4 v128, s[30:31]
	s_add_i32 m0, s41, 0xe000
	s_nop 0
	global_load_lds_dwordx4 v130, s[30:31]
	s_and_b64 vcc, exec, s[14:15]
	s_cbranch_vccnz .Lmy_lw_5
	s_cmp_lg_u32 s101, 0
	s_cbranch_scc1 .Lmy_rx_1
	s_waitcnt vmcnt(8)
	s_branch .Lmy_ry_1
.Lmy_rx_1:
	s_waitcnt vmcnt(16)
.Lmy_ry_1:
.Lmy_lw_5:
	s_waitcnt lgkmcnt(0)
	s_barrier
	s_setprio 1
	s_waitcnt lgkmcnt(0)
	v_mfma_scale_f32_16x16x128_f8f6f4 v[124:127], v[142:149], v[174:181], v[124:127], v141, v141 op_sel_hi:[0,0,0]
	v_mfma_scale_f32_16x16x128_f8f6f4 v[116:119], v[150:157], v[174:181], v[116:119], v141, v141 op_sel_hi:[0,0,0]
	v_mfma_scale_f32_16x16x128_f8f6f4 v[108:111], v[142:149], v[182:189], v[108:111], v141, v141 op_sel_hi:[0,0,0]
	v_mfma_scale_f32_16x16x128_f8f6f4 v[100:103], v[150:157], v[182:189], v[100:103], v141, v141 op_sel_hi:[0,0,0]
	v_mfma_scale_f32_16x16x128_f8f6f4 v[206:209], v[142:149], v[190:197], v[92:95], v141, v141 op_sel_hi:[0,0,0]
	v_mfma_scale_f32_16x16x128_f8f6f4 v[210:213], v[150:157], v[190:197], v[84:87], v141, v141 op_sel_hi:[0,0,0]
	v_mfma_scale_f32_16x16x128_f8f6f4 v[214:217], v[142:149], v[198:205], v[76:79], v141, v141 op_sel_hi:[0,0,0]
	v_mfma_scale_f32_16x16x128_f8f6f4 v[218:221], v[150:157], v[198:205], v[68:71], v141, v141 op_sel_hi:[0,0,0]
	s_setprio 0
	s_setprio 1
	v_mfma_scale_f32_16x16x128_f8f6f4 v[120:123], v[158:165], v[174:181], v[120:123], v141, v141 op_sel_hi:[0,0,0]
	v_mfma_scale_f32_16x16x128_f8f6f4 v[112:115], v[166:173], v[174:181], v[112:115], v141, v141 op_sel_hi:[0,0,0]
	v_mfma_scale_f32_16x16x128_f8f6f4 v[104:107], v[158:165], v[182:189], v[104:107], v141, v141 op_sel_hi:[0,0,0]
	v_mfma_scale_f32_16x16x128_f8f6f4 v[96:99], v[166:173], v[182:189], v[96:99], v141, v141 op_sel_hi:[0,0,0]
	v_mfma_scale_f32_16x16x128_f8f6f4 v[174:177], v[158:165], v[190:197], v[88:91], v141, v141 op_sel_hi:[0,0,0]
	v_mfma_scale_f32_16x16x128_f8f6f4 v[178:181], v[166:173], v[190:197], v[80:83], v141, v141 op_sel_hi:[0,0,0]
	v_mfma_scale_f32_16x16x128_f8f6f4 v[182:185], v[158:165], v[198:205], v[72:75], v141, v141 op_sel_hi:[0,0,0]
	v_mfma_scale_f32_16x16x128_f8f6f4 v[186:189], v[166:173], v[198:205], v[64:67], v141, v141 op_sel_hi:[0,0,0]
	s_setprio 0
	s_cmp_lg_u32 s101, 0
	s_cbranch_scc1 .Lmy_rx_2
	s_waitcnt vmcnt(8)
	s_branch .Lmy_ry_2

.Lmy_ry_2:
	s_barrier
	s_add_i32 s64, s54, s3
	v_mov_b32_e32 v128, v135
	v_mov_b32_e32 v130, v136
	s_mov_b32 m0, s64
	s_nop 0
	ds_read_b128 v[64:67], v140 offset:16384
	ds_read_b128 v[68:71], v140 offset:17408
	ds_read_b128 v[72:75], v140 offset:18432
	ds_read_b128 v[76:79], v140 offset:19456
	ds_read_b128 v[80:83], v140 offset:20480
	ds_read_b128 v[84:87], v140 offset:21504
	ds_read_b128 v[88:91], v140 offset:22528
	ds_read_b128 v[92:95], v140 offset:23552
	v_mov_b32_e32 v131, v129
	global_load_lds_dwordx4 v128, s[36:37]
	s_add_i32 m0, s64, 0x2000
	v_mov_b32_e32 v128, v135
	global_load_lds_dwordx4 v130, s[36:37]
	v_mov_b32_e32 v130, v136
	s_add_i32 s64, s55, s3
	v_lshl_add_u64 v[190:191], s[36:37], 0, v[128:129]
	v_lshl_add_u64 v[190:191], v[190:191], 0, s[8:9]
	s_mov_b32 m0, s64
	v_lshl_add_u64 v[130:131], s[36:37], 0, v[130:131]
	global_load_lds_dwordx4 v[190:191], off
	v_lshl_add_u64 v[130:131], v[130:131], 0, s[8:9]
	s_add_i32 m0, s64, 0x2000
	v_mov_b32_e32 v128, v133
	global_load_lds_dwordx4 v[130:131], off
	v_mov_b32_e32 v130, v134
	s_mov_b32 m0, s41
	s_nop 0
	global_load_lds_dwordx4 v128, s[34:35]
	s_mov_b32 m0, s42
	s_nop 0
	global_load_lds_dwordx4 v130, s[34:35]
	s_and_b64 vcc, exec, s[14:15]
	s_cbranch_vccnz .Lmy_lw_6
	s_cmp_lg_u32 s101, 0
	s_cbranch_scc1 .Lmy_rx_3
	s_waitcnt vmcnt(8)
	s_branch .Lmy_ry_3

.Lmy_ry_3:
.Lmy_lw_6:
	s_waitcnt lgkmcnt(0)
	s_barrier
	s_setprio 1
	s_waitcnt lgkmcnt(0)
	v_mfma_scale_f32_16x16x128_f8f6f4 v[60:63], v[142:149], v[64:71], v[60:63], v141, v141 op_sel_hi:[0,0,0]
	v_mfma_scale_f32_16x16x128_f8f6f4 v[52:55], v[150:157], v[64:71], v[52:55], v141, v141 op_sel_hi:[0,0,0]
	v_mfma_scale_f32_16x16x128_f8f6f4 v[44:47], v[142:149], v[72:79], v[44:47], v141, v141 op_sel_hi:[0,0,0]
	v_mfma_scale_f32_16x16x128_f8f6f4 v[198:201], v[150:157], v[72:79], v[36:39], v141, v141 op_sel_hi:[0,0,0]
	v_mfma_scale_f32_16x16x128_f8f6f4 v[202:205], v[142:149], v[80:87], v[28:31], v141, v141 op_sel_hi:[0,0,0]
	v_mfma_scale_f32_16x16x128_f8f6f4 v[222:225], v[150:157], v[80:87], v[20:23], v141, v141 op_sel_hi:[0,0,0]
	v_mfma_scale_f32_16x16x128_f8f6f4 v[226:229], v[142:149], v[88:95], v[12:15], v141, v141 op_sel_hi:[0,0,0]
	v_mfma_scale_f32_16x16x128_f8f6f4 v[230:233], v[150:157], v[88:95], v[4:7], v141, v141 op_sel_hi:[0,0,0]
	s_setprio 0
	s_setprio 1
	v_mfma_scale_f32_16x16x128_f8f6f4 v[56:59], v[158:165], v[64:71], v[56:59], v141, v141 op_sel_hi:[0,0,0]
	v_mfma_scale_f32_16x16x128_f8f6f4 v[48:51], v[166:173], v[64:71], v[48:51], v141, v141 op_sel_hi:[0,0,0]
	v_mfma_scale_f32_16x16x128_f8f6f4 v[40:43], v[158:165], v[72:79], v[40:43], v141, v141 op_sel_hi:[0,0,0]
	v_mfma_scale_f32_16x16x128_f8f6f4 v[234:237], v[166:173], v[72:79], v[32:35], v141, v141 op_sel_hi:[0,0,0]
	v_mfma_scale_f32_16x16x128_f8f6f4 v[238:241], v[158:165], v[80:87], v[24:27], v141, v141 op_sel_hi:[0,0,0]
	v_mfma_scale_f32_16x16x128_f8f6f4 v[242:245], v[166:173], v[80:87], v[16:19], v141, v141 op_sel_hi:[0,0,0]
	v_mfma_scale_f32_16x16x128_f8f6f4 v[246:249], v[158:165], v[88:95], v[8:11], v141, v141 op_sel_hi:[0,0,0]
	v_mfma_scale_f32_16x16x128_f8f6f4 v[250:253], v[166:173], v[88:95], v[0:3], v141, v141 op_sel_hi:[0,0,0]
	s_setprio 0
	s_cmp_lg_u32 s101, 0
	s_cbranch_scc1 .Lmy_rx_4
	s_waitcnt vmcnt(8)
	s_branch .Lmy_ry_4

.Lmy_ry_4:
	s_mov_b32 s101, 0
	s_barrier
	s_add_i32 s66, 0, 0x18000
	s_nop 2
	v_add_u32_e32 v8, s66, v137
	s_add_i32 s67, 0, 0x1c000
	ds_read_b128 v[0:3], v8
	ds_read_b128 v[4:7], v8 offset:1024
	ds_read_b128 v[142:145], v8 offset:2048
	ds_read_b128 v[146:149], v8 offset:3072
	v_add_u32_e32 v8, s67, v137
	ds_read_b128 v[150:153], v8
	ds_read_b128 v[154:157], v8 offset:1024
	ds_read_b128 v[158:161], v8 offset:2048
	ds_read_b128 v[162:165], v8 offset:3072
	s_add_u32 s64, s34, 0x40000
	v_mov_b32_e32 v64, v133
	v_mov_b32_e32 v65, v134
	s_addc_u32 s65, s35, 0
	s_mov_b32 m0, s43
	ds_read_b128 v[8:11], v140 offset:32768
	ds_read_b128 v[12:15], v140 offset:33792
	ds_read_b128 v[16:19], v140 offset:34816
	ds_read_b128 v[20:23], v140 offset:35840
	ds_read_b128 v[24:27], v140 offset:36864
	ds_read_b128 v[28:31], v140 offset:37888
	ds_read_b128 v[32:35], v140 offset:38912
	ds_read_b128 v[36:39], v140 offset:39936
	s_nop 0
	global_load_lds_dwordx4 v64, s[64:65]
	s_mov_b32 m0, s44
	s_nop 0
	global_load_lds_dwordx4 v65, s[64:65]
	s_and_b64 vcc, exec, s[14:15]
	s_cbranch_vccnz .Lmy_lw_7
	s_waitcnt vmcnt(8)

.LBB0_1683:
	s_mov_b32 s101, 1
	v_mov_b32_e32 v142, v124
	v_mov_b32_e32 v143, v120
	v_pk_mul_f32 v[142:143], v[142:143], s[18:19] op_sel_hi:[1,0]
	v_mov_b32_e32 v128, v132
	v_mul_f32_e32 v120, 0xbfb8aa3b, v142
	v_exp_f32_e32 v120, v120
	s_lshl_b32 s21, s28, 8
	s_add_i32 s21, s21, s45
	v_add_f32_e32 v120, 1.0, v120
	v_ashrrev_i32_e32 v130, 1, v128
	v_and_or_b32 v124, v128, 15, s21
	v_rcp_f32_e32 v128, v120
	v_mov_b32_e32 v120, v125
	v_pk_mul_f32 v[120:121], v[120:121], s[18:19] op_sel_hi:[1,0]
	v_mul_f32_e32 v142, v142, v143
	v_mul_f32_e32 v125, 0xbfb8aa3b, v120
	v_exp_f32_e32 v125, v125
	v_mul_f32_e32 v128, v128, v142
	v_mov_b32_e32 v142, v126
	v_mov_b32_e32 v143, v122
	v_pk_mul_f32 v[142:143], v[142:143], s[18:19] op_sel_hi:[1,0]
	v_add_f32_e32 v125, 1.0, v125
	v_mul_f32_e32 v122, 0xbfb8aa3b, v142
	v_rcp_f32_e32 v125, v125
	v_exp_f32_e32 v122, v122
	v_mul_f32_e32 v120, v120, v121
	v_mul_f32_e32 v126, v142, v143
	v_mul_f32_e32 v125, v125, v120
	v_add_f32_e32 v120, 1.0, v122
	v_mov_b32_e32 v122, v127
	v_rcp_f32_e32 v142, v120
	v_pk_mul_f32 v[120:121], v[122:123], s[18:19] op_sel_hi:[1,0]
	v_mov_b32_e32 v123, v112
	v_mul_f32_e32 v122, 0xbfb8aa3b, v120
	v_exp_f32_e32 v127, v122
	v_mov_b32_e32 v122, v116
	v_pk_mul_f32 v[122:123], v[122:123], s[18:19] op_sel_hi:[1,0]
	v_mul_f32_e32 v120, v120, v121
	v_mul_f32_e32 v112, 0xbfb8aa3b, v122
	v_exp_f32_e32 v112, v112
	v_add_f32_e32 v116, 1.0, v127
	v_rcp_f32_e32 v116, v116
	v_mul_f32_e32 v126, v142, v126
	v_add_f32_e32 v112, 1.0, v112
	v_rcp_f32_e32 v112, v112
	v_mul_f32_e32 v120, v116, v120
	v_mul_f32_e32 v116, v122, v123
	v_and_b32_e32 v130, -8, v130
	v_mul_f32_e32 v121, v112, v116
	v_mov_b32_e32 v112, v117
	v_pk_mul_f32 v[112:113], v[112:113], s[18:19] op_sel_hi:[1,0]
	v_mov_b32_e32 v117, v114
	v_mul_f32_e32 v116, 0xbfb8aa3b, v112
	v_exp_f32_e32 v122, v116
	v_mov_b32_e32 v116, v118
	v_pk_mul_f32 v[116:117], v[116:117], s[18:19] op_sel_hi:[1,0]
	v_mul_f32_e32 v118, v112, v113
	v_mul_f32_e32 v114, 0xbfb8aa3b, v116
	v_exp_f32_e32 v114, v114
	v_add_f32_e32 v112, 1.0, v122
	v_rcp_f32_e32 v122, v112
	s_lshl_b32 s28, s29, 7
	v_add_f32_e32 v112, 1.0, v114
	v_mov_b32_e32 v114, v119
	v_rcp_f32_e32 v123, v112
	v_pk_mul_f32 v[112:113], v[114:115], s[18:19] op_sel_hi:[1,0]
	v_mul_f32_e32 v115, v116, v117
	v_mul_f32_e32 v114, 0xbfb8aa3b, v112
	v_exp_f32_e32 v114, v114
	v_mul_f32_e32 v118, v122, v118
	v_mul_f32_e32 v116, v123, v115
	v_mov_b32_e32 v115, v129
	v_add_f32_e32 v114, 1.0, v114
	v_rcp_f32_e32 v117, v114
	v_cvt_pk_fp8_f32 v115, v121, v118
	v_mul_f32_e32 v112, v112, v113
	v_mov_b32_e32 v114, v129
	v_mul_f32_e32 v112, v117, v112
	v_cvt_pk_fp8_f32 v115, v116, v112 op_sel:[0,0,1]
	v_mov_b32_e32 v116, v108
	v_mov_b32_e32 v117, v104
	v_pk_mul_f32 v[116:117], v[116:117], s[18:19] op_sel_hi:[1,0]
	v_cvt_pk_fp8_f32 v114, v128, v125
	v_mul_f32_e32 v104, 0xbfb8aa3b, v116
	v_exp_f32_e32 v104, v104
	v_ashrrev_i32_e32 v125, 31, v124
	v_cvt_pk_fp8_f32 v114, v126, v120 op_sel:[0,0,1]
	v_lshlrev_b64 v[112:113], 11, v[124:125]
	v_add_f32_e32 v104, 1.0, v104
	v_rcp_f32_e32 v108, v104
	v_mov_b32_e32 v104, v109
	v_pk_mul_f32 v[104:105], v[104:105], s[18:19] op_sel_hi:[1,0]
	v_add_u32_e32 v130, s46, v130
	v_mul_f32_e32 v109, 0xbfb8aa3b, v104
	s_ashr_i32 s29, s28, 31
	v_lshl_add_u64 v[112:113], s[16:17], 0, v[112:113]
	v_exp_f32_e32 v109, v109
	v_ashrrev_i32_e32 v131, 31, v130
	v_lshl_add_u64 v[112:113], v[112:113], 0, s[28:29]
	v_lshl_add_u64 v[112:113], v[112:113], 0, v[130:131]
	global_store_dwordx2 v[112:113], v[114:115], off
	v_mul_f32_e32 v112, v116, v117
	v_mul_f32_e32 v112, v108, v112
	v_add_f32_e32 v108, 1.0, v109
	v_rcp_f32_e32 v113, v108
	v_mov_b32_e32 v108, v110
	v_mov_b32_e32 v109, v106
	v_pk_mul_f32 v[108:109], v[108:109], s[18:19] op_sel_hi:[1,0]
	v_mul_f32_e32 v104, v104, v105
	v_mul_f32_e32 v106, 0xbfb8aa3b, v108
	v_exp_f32_e32 v106, v106
	v_mul_f32_e32 v110, v113, v104
	v_mul_f32_e32 v108, v108, v109
	s_andn2_b64 vcc, exec, s[26:27]
	v_add_f32_e32 v104, 1.0, v106
	v_mov_b32_e32 v106, v111
	v_rcp_f32_e32 v109, v104
	v_pk_mul_f32 v[104:105], v[106:107], s[18:19] op_sel_hi:[1,0]
	v_mov_b32_e32 v107, v96
	v_mul_f32_e32 v106, 0xbfb8aa3b, v104
	v_exp_f32_e32 v111, v106
	v_mov_b32_e32 v106, v100
	v_pk_mul_f32 v[106:107], v[106:107], s[18:19] op_sel_hi:[1,0]
	v_mul_f32_e32 v104, v104, v105
	v_mul_f32_e32 v96, 0xbfb8aa3b, v106
	v_exp_f32_e32 v96, v96
	v_add_f32_e32 v100, 1.0, v111
	v_rcp_f32_e32 v100, v100
	v_mul_f32_e32 v108, v109, v108
	v_add_f32_e32 v96, 1.0, v96
	v_rcp_f32_e32 v96, v96
	v_mul_f32_e32 v104, v100, v104
	v_mul_f32_e32 v100, v106, v107
	s_mov_b64 s[26:27], -1
	v_mul_f32_e32 v105, v96, v100
	v_mov_b32_e32 v96, v101
	v_pk_mul_f32 v[96:97], v[96:97], s[18:19] op_sel_hi:[1,0]
	v_mov_b32_e32 v101, v98
	v_mul_f32_e32 v100, 0xbfb8aa3b, v96
	v_exp_f32_e32 v106, v100
	v_mov_b32_e32 v100, v102
	v_pk_mul_f32 v[100:101], v[100:101], s[18:19] op_sel_hi:[1,0]
	v_mul_f32_e32 v102, v96, v97
	v_mul_f32_e32 v98, 0xbfb8aa3b, v100
	v_exp_f32_e32 v98, v98
	v_add_f32_e32 v96, 1.0, v106
	v_rcp_f32_e32 v106, v96
	v_add_f32_e32 v96, 1.0, v98
	v_mov_b32_e32 v98, v103
	v_rcp_f32_e32 v107, v96
	v_pk_mul_f32 v[96:97], v[98:99], s[18:19] op_sel_hi:[1,0]
	v_mul_f32_e32 v99, v100, v101
	v_mul_f32_e32 v98, 0xbfb8aa3b, v96
	v_exp_f32_e32 v98, v98
	v_mul_f32_e32 v102, v106, v102
	v_mul_f32_e32 v100, v107, v99
	v_mov_b32_e32 v99, v129
	v_add_f32_e32 v98, 1.0, v98
	v_rcp_f32_e32 v101, v98
	v_cvt_pk_fp8_f32 v99, v105, v102
	v_mul_f32_e32 v96, v96, v97
	v_mov_b32_e32 v98, v129
	v_mul_f32_e32 v96, v101, v96
	v_cvt_pk_fp8_f32 v99, v100, v96 op_sel:[0,0,1]
	v_mov_b32_e32 v100, v92
	v_mov_b32_e32 v101, v88
	v_pk_mul_f32 v[100:101], v[100:101], s[18:19] op_sel_hi:[1,0]
	v_cvt_pk_fp8_f32 v98, v112, v110
	v_mul_f32_e32 v88, 0xbfb8aa3b, v100
	v_exp_f32_e32 v88, v88
	v_or_b32_e32 v96, 16, v124
	v_ashrrev_i32_e32 v97, 31, v96
	v_cvt_pk_fp8_f32 v98, v108, v104 op_sel:[0,0,1]
	v_add_f32_e32 v88, 1.0, v88
	v_rcp_f32_e32 v92, v88
	v_mov_b32_e32 v88, v93
	v_pk_mul_f32 v[88:89], v[88:89], s[18:19] op_sel_hi:[1,0]
	v_lshlrev_b64 v[96:97], 11, v[96:97]
	v_mul_f32_e32 v93, 0xbfb8aa3b, v88
	v_lshl_add_u64 v[96:97], s[16:17], 0, v[96:97]
	v_exp_f32_e32 v93, v93
	v_lshl_add_u64 v[96:97], v[96:97], 0, s[28:29]
	v_lshl_add_u64 v[96:97], v[96:97], 0, v[130:131]
	global_store_dwordx2 v[96:97], v[98:99], off
	v_mul_f32_e32 v96, v100, v101
	v_mul_f32_e32 v96, v92, v96
	v_add_f32_e32 v92, 1.0, v93
	v_rcp_f32_e32 v97, v92
	v_mov_b32_e32 v92, v94
	v_mov_b32_e32 v93, v90
	v_pk_mul_f32 v[92:93], v[92:93], s[18:19] op_sel_hi:[1,0]
	v_mul_f32_e32 v88, v88, v89
	v_mul_f32_e32 v90, 0xbfb8aa3b, v92
	v_exp_f32_e32 v90, v90
	v_mul_f32_e32 v94, v97, v88
	v_mul_f32_e32 v92, v92, v93
	v_add_f32_e32 v88, 1.0, v90
	v_mov_b32_e32 v90, v95
	v_rcp_f32_e32 v93, v88
	v_pk_mul_f32 v[88:89], v[90:91], s[18:19] op_sel_hi:[1,0]
	v_mov_b32_e32 v91, v80
	v_mul_f32_e32 v90, 0xbfb8aa3b, v88
	v_exp_f32_e32 v95, v90
	v_mov_b32_e32 v90, v84
	v_pk_mul_f32 v[90:91], v[90:91], s[18:19] op_sel_hi:[1,0]
	v_mul_f32_e32 v88, v88, v89
	v_mul_f32_e32 v80, 0xbfb8aa3b, v90
	v_exp_f32_e32 v80, v80
	v_add_f32_e32 v84, 1.0, v95
	v_rcp_f32_e32 v84, v84
	v_mul_f32_e32 v92, v93, v92
	v_add_f32_e32 v80, 1.0, v80
	v_rcp_f32_e32 v80, v80
	v_mul_f32_e32 v88, v84, v88
	v_mul_f32_e32 v84, v90, v91
	v_mul_f32_e32 v89, v80, v84
	v_mov_b32_e32 v80, v85
	v_pk_mul_f32 v[80:81], v[80:81], s[18:19] op_sel_hi:[1,0]
	v_mov_b32_e32 v85, v82
	v_mul_f32_e32 v84, 0xbfb8aa3b, v80
	v_exp_f32_e32 v90, v84
	v_mov_b32_e32 v84, v86
	v_pk_mul_f32 v[84:85], v[84:85], s[18:19] op_sel_hi:[1,0]
	v_mul_f32_e32 v86, v80, v81
	v_mul_f32_e32 v82, 0xbfb8aa3b, v84
	v_exp_f32_e32 v82, v82
	v_add_f32_e32 v80, 1.0, v90
	v_rcp_f32_e32 v90, v80
	v_add_f32_e32 v80, 1.0, v82
	v_mov_b32_e32 v82, v87
	v_rcp_f32_e32 v91, v80
	v_pk_mul_f32 v[80:81], v[82:83], s[18:19] op_sel_hi:[1,0]
	v_mul_f32_e32 v83, v84, v85
	v_mul_f32_e32 v82, 0xbfb8aa3b, v80
	v_exp_f32_e32 v82, v82
	v_mul_f32_e32 v86, v90, v86
	v_mul_f32_e32 v84, v91, v83
	v_mov_b32_e32 v83, v129
	v_add_f32_e32 v82, 1.0, v82
	v_rcp_f32_e32 v85, v82
	v_cvt_pk_fp8_f32 v83, v89, v86
	v_mul_f32_e32 v80, v80, v81
	v_mov_b32_e32 v82, v129
	v_mul_f32_e32 v80, v85, v80
	v_cvt_pk_fp8_f32 v83, v84, v80 op_sel:[0,0,1]
	v_mov_b32_e32 v84, v76
	v_mov_b32_e32 v85, v72
	v_pk_mul_f32 v[84:85], v[84:85], s[18:19] op_sel_hi:[1,0]
	v_cvt_pk_fp8_f32 v82, v96, v94
	v_mul_f32_e32 v72, 0xbfb8aa3b, v84
	v_exp_f32_e32 v72, v72
	v_or_b32_e32 v80, 32, v124
	v_ashrrev_i32_e32 v81, 31, v80
	v_cvt_pk_fp8_f32 v82, v92, v88 op_sel:[0,0,1]
	v_add_f32_e32 v72, 1.0, v72
	v_rcp_f32_e32 v76, v72
	v_mov_b32_e32 v72, v77
	v_pk_mul_f32 v[72:73], v[72:73], s[18:19] op_sel_hi:[1,0]
	v_lshlrev_b64 v[80:81], 11, v[80:81]
	v_mul_f32_e32 v77, 0xbfb8aa3b, v72
	v_lshl_add_u64 v[80:81], s[16:17], 0, v[80:81]
	v_exp_f32_e32 v77, v77
	v_lshl_add_u64 v[80:81], v[80:81], 0, s[28:29]
	v_lshl_add_u64 v[80:81], v[80:81], 0, v[130:131]
	global_store_dwordx2 v[80:81], v[82:83], off
	v_mul_f32_e32 v80, v84, v85
	v_mul_f32_e32 v80, v76, v80
	v_add_f32_e32 v76, 1.0, v77
	v_rcp_f32_e32 v81, v76
	v_mov_b32_e32 v76, v78
	v_mov_b32_e32 v77, v74
	v_pk_mul_f32 v[76:77], v[76:77], s[18:19] op_sel_hi:[1,0]
	v_mul_f32_e32 v72, v72, v73
	v_mul_f32_e32 v74, 0xbfb8aa3b, v76
	v_exp_f32_e32 v74, v74
	v_mul_f32_e32 v78, v81, v72
	v_mul_f32_e32 v76, v76, v77
	v_add_f32_e32 v72, 1.0, v74
	v_mov_b32_e32 v74, v79
	v_rcp_f32_e32 v77, v72
	v_pk_mul_f32 v[72:73], v[74:75], s[18:19] op_sel_hi:[1,0]
	v_mov_b32_e32 v75, v64
	v_mul_f32_e32 v74, 0xbfb8aa3b, v72
	v_exp_f32_e32 v79, v74
	v_mov_b32_e32 v74, v68
	v_pk_mul_f32 v[74:75], v[74:75], s[18:19] op_sel_hi:[1,0]
	v_mul_f32_e32 v72, v72, v73
	v_mul_f32_e32 v64, 0xbfb8aa3b, v74
	v_exp_f32_e32 v64, v64
	v_add_f32_e32 v68, 1.0, v79
	v_rcp_f32_e32 v68, v68
	v_mul_f32_e32 v76, v77, v76
	v_add_f32_e32 v64, 1.0, v64
	v_rcp_f32_e32 v64, v64
	v_mul_f32_e32 v72, v68, v72
	v_mul_f32_e32 v68, v74, v75
	v_mul_f32_e32 v73, v64, v68
	v_mov_b32_e32 v64, v69
	v_pk_mul_f32 v[64:65], v[64:65], s[18:19] op_sel_hi:[1,0]
	v_mov_b32_e32 v69, v66
	v_mul_f32_e32 v68, 0xbfb8aa3b, v64
	v_exp_f32_e32 v74, v68
	v_mov_b32_e32 v68, v70
	v_pk_mul_f32 v[68:69], v[68:69], s[18:19] op_sel_hi:[1,0]
	v_mul_f32_e32 v70, v64, v65
	v_mul_f32_e32 v66, 0xbfb8aa3b, v68
	v_exp_f32_e32 v66, v66
	v_add_f32_e32 v64, 1.0, v74
	v_rcp_f32_e32 v74, v64
	v_add_f32_e32 v64, 1.0, v66
	v_mov_b32_e32 v66, v71
	v_rcp_f32_e32 v75, v64
	v_pk_mul_f32 v[64:65], v[66:67], s[18:19] op_sel_hi:[1,0]
	v_mul_f32_e32 v67, v68, v69
	v_mul_f32_e32 v66, 0xbfb8aa3b, v64
	v_exp_f32_e32 v66, v66
	v_mul_f32_e32 v70, v74, v70
	v_mul_f32_e32 v68, v75, v67
	v_mov_b32_e32 v67, v129
	v_add_f32_e32 v66, 1.0, v66
	v_rcp_f32_e32 v69, v66
	v_cvt_pk_fp8_f32 v67, v73, v70
	v_mul_f32_e32 v64, v64, v65
	v_mov_b32_e32 v66, v129
	v_mul_f32_e32 v64, v69, v64
	v_cvt_pk_fp8_f32 v66, v80, v78
	v_cvt_pk_fp8_f32 v67, v68, v64 op_sel:[0,0,1]
	v_mov_b32_e32 v68, v60
	v_mov_b32_e32 v69, v56
	v_pk_mul_f32 v[68:69], v[68:69], s[18:19] op_sel_hi:[1,0]
	v_or_b32_e32 v64, 48, v124
	v_mul_f32_e32 v56, 0xbfb8aa3b, v68
	v_ashrrev_i32_e32 v65, 31, v64
	v_exp_f32_e32 v56, v56
	v_cvt_pk_fp8_f32 v66, v76, v72 op_sel:[0,0,1]
	v_lshlrev_b64 v[64:65], 11, v[64:65]
	v_lshl_add_u64 v[64:65], s[16:17], 0, v[64:65]
	v_lshl_add_u64 v[64:65], v[64:65], 0, s[28:29]
	v_lshl_add_u64 v[64:65], v[64:65], 0, v[130:131]
	v_add_f32_e32 v56, 1.0, v56
	global_store_dwordx2 v[64:65], v[66:67], off
	v_rcp_f32_e32 v64, v56
	v_mov_b32_e32 v56, v61
	v_pk_mul_f32 v[56:57], v[56:57], s[18:19] op_sel_hi:[1,0]
	v_mul_f32_e32 v65, v68, v69
	v_mul_f32_e32 v60, 0xbfb8aa3b, v56
	v_exp_f32_e32 v61, v60
	v_mul_f32_e32 v66, v64, v65
	v_mov_b32_e32 v64, v62
	v_mov_b32_e32 v65, v58
	v_pk_mul_f32 v[64:65], v[64:65], s[18:19] op_sel_hi:[1,0]
	v_add_f32_e32 v61, 1.0, v61
	v_mul_f32_e32 v58, 0xbfb8aa3b, v64
	v_rcp_f32_e32 v61, v61
	v_exp_f32_e32 v58, v58
	v_mul_f32_e32 v56, v56, v57
	v_mul_f32_e32 v62, v64, v65
	v_mul_f32_e32 v61, v61, v56
	v_add_f32_e32 v56, 1.0, v58
	v_mov_b32_e32 v58, v63
	v_rcp_f32_e32 v64, v56
	v_pk_mul_f32 v[56:57], v[58:59], s[18:19] op_sel_hi:[1,0]
	v_mov_b32_e32 v59, v48
	v_mul_f32_e32 v58, 0xbfb8aa3b, v56
	v_exp_f32_e32 v63, v58
	v_mov_b32_e32 v58, v52
	v_pk_mul_f32 v[58:59], v[58:59], s[18:19] op_sel_hi:[1,0]
	v_mul_f32_e32 v56, v56, v57
	v_mul_f32_e32 v48, 0xbfb8aa3b, v58
	v_exp_f32_e32 v48, v48
	v_add_f32_e32 v52, 1.0, v63
	v_rcp_f32_e32 v52, v52
	v_add_u32_e32 v60, 0x80, v124
	v_add_f32_e32 v48, 1.0, v48
	v_rcp_f32_e32 v48, v48
	v_mul_f32_e32 v56, v52, v56
	v_mul_f32_e32 v52, v58, v59
	v_mul_f32_e32 v62, v64, v62
	v_mul_f32_e32 v57, v48, v52
	v_mov_b32_e32 v48, v53
	v_pk_mul_f32 v[48:49], v[48:49], s[18:19] op_sel_hi:[1,0]
	v_mov_b32_e32 v53, v50
	v_mul_f32_e32 v52, 0xbfb8aa3b, v48
	v_exp_f32_e32 v58, v52
	v_mov_b32_e32 v52, v54
	v_pk_mul_f32 v[52:53], v[52:53], s[18:19] op_sel_hi:[1,0]
	v_mul_f32_e32 v54, v48, v49
	v_mul_f32_e32 v50, 0xbfb8aa3b, v52
	v_exp_f32_e32 v50, v50
	v_add_f32_e32 v48, 1.0, v58
	v_rcp_f32_e32 v58, v48
	v_add_f32_e32 v48, 1.0, v50
	v_mov_b32_e32 v50, v55
	v_rcp_f32_e32 v59, v48
	v_pk_mul_f32 v[48:49], v[50:51], s[18:19] op_sel_hi:[1,0]
	v_mul_f32_e32 v51, v52, v53
	v_mul_f32_e32 v50, 0xbfb8aa3b, v48
	v_exp_f32_e32 v50, v50
	v_mul_f32_e32 v54, v58, v54
	v_mul_f32_e32 v52, v59, v51
	v_mov_b32_e32 v51, v129
	v_add_f32_e32 v50, 1.0, v50
	v_rcp_f32_e32 v53, v50
	v_cvt_pk_fp8_f32 v51, v57, v54
	v_mul_f32_e32 v48, v48, v49
	v_mov_b32_e32 v50, v129
	v_mul_f32_e32 v48, v53, v48
	v_cvt_pk_fp8_f32 v51, v52, v48 op_sel:[0,0,1]
	v_mov_b32_e32 v52, v44
	v_mov_b32_e32 v53, v40
	v_pk_mul_f32 v[52:53], v[52:53], s[18:19] op_sel_hi:[1,0]
	v_cvt_pk_fp8_f32 v50, v66, v61
	v_mul_f32_e32 v40, 0xbfb8aa3b, v52
	v_exp_f32_e32 v40, v40
	v_ashrrev_i32_e32 v61, 31, v60
	v_cvt_pk_fp8_f32 v50, v62, v56 op_sel:[0,0,1]
	v_lshlrev_b64 v[48:49], 11, v[60:61]
	v_add_f32_e32 v40, 1.0, v40
	v_rcp_f32_e32 v44, v40
	v_mov_b32_e32 v40, v45
	v_pk_mul_f32 v[40:41], v[40:41], s[18:19] op_sel_hi:[1,0]
	v_lshl_add_u64 v[48:49], s[16:17], 0, v[48:49]
	v_mul_f32_e32 v45, 0xbfb8aa3b, v40
	v_exp_f32_e32 v45, v45
	v_lshl_add_u64 v[48:49], v[48:49], 0, s[28:29]
	v_lshl_add_u64 v[48:49], v[48:49], 0, v[130:131]
	global_store_dwordx2 v[48:49], v[50:51], off
	v_mul_f32_e32 v48, v52, v53
	v_mul_f32_e32 v48, v44, v48
	v_add_f32_e32 v44, 1.0, v45
	v_rcp_f32_e32 v49, v44
	v_mov_b32_e32 v44, v46
	v_mov_b32_e32 v45, v42
	v_pk_mul_f32 v[44:45], v[44:45], s[18:19] op_sel_hi:[1,0]
	v_mul_f32_e32 v40, v40, v41
	v_mul_f32_e32 v42, 0xbfb8aa3b, v44
	v_exp_f32_e32 v42, v42
	v_mul_f32_e32 v46, v49, v40
	v_mul_f32_e32 v44, v44, v45
	v_add_f32_e32 v40, 1.0, v42
	v_mov_b32_e32 v42, v47
	v_rcp_f32_e32 v45, v40
	v_pk_mul_f32 v[40:41], v[42:43], s[18:19] op_sel_hi:[1,0]
	v_mov_b32_e32 v43, v32
	v_mul_f32_e32 v42, 0xbfb8aa3b, v40
	v_exp_f32_e32 v47, v42
	v_mov_b32_e32 v42, v36
	v_pk_mul_f32 v[42:43], v[42:43], s[18:19] op_sel_hi:[1,0]
	v_mul_f32_e32 v40, v40, v41
	v_mul_f32_e32 v32, 0xbfb8aa3b, v42
	v_exp_f32_e32 v32, v32
	v_add_f32_e32 v36, 1.0, v47
	v_rcp_f32_e32 v36, v36
	v_mul_f32_e32 v44, v45, v44
	v_add_f32_e32 v32, 1.0, v32
	v_rcp_f32_e32 v32, v32
	v_mul_f32_e32 v40, v36, v40
	v_mul_f32_e32 v36, v42, v43
	v_mul_f32_e32 v41, v32, v36
	v_mov_b32_e32 v32, v37
	v_pk_mul_f32 v[32:33], v[32:33], s[18:19] op_sel_hi:[1,0]
	v_mov_b32_e32 v37, v34
	v_mul_f32_e32 v36, 0xbfb8aa3b, v32
	v_exp_f32_e32 v42, v36
	v_mov_b32_e32 v36, v38
	v_pk_mul_f32 v[36:37], v[36:37], s[18:19] op_sel_hi:[1,0]
	v_mul_f32_e32 v38, v32, v33
	v_mul_f32_e32 v34, 0xbfb8aa3b, v36
	v_exp_f32_e32 v34, v34
	v_add_f32_e32 v32, 1.0, v42
	v_rcp_f32_e32 v42, v32
	v_add_f32_e32 v32, 1.0, v34
	v_mov_b32_e32 v34, v39
	v_rcp_f32_e32 v43, v32
	v_pk_mul_f32 v[32:33], v[34:35], s[18:19] op_sel_hi:[1,0]
	v_mul_f32_e32 v35, v36, v37
	v_mul_f32_e32 v34, 0xbfb8aa3b, v32
	v_exp_f32_e32 v34, v34
	v_mul_f32_e32 v38, v42, v38
	v_mul_f32_e32 v36, v43, v35
	v_mov_b32_e32 v35, v129
	v_add_f32_e32 v34, 1.0, v34
	v_rcp_f32_e32 v37, v34
	v_cvt_pk_fp8_f32 v35, v41, v38
	v_mul_f32_e32 v32, v32, v33
	v_mov_b32_e32 v34, v129
	v_mul_f32_e32 v32, v37, v32
	v_cvt_pk_fp8_f32 v35, v36, v32 op_sel:[0,0,1]
	v_mov_b32_e32 v36, v28
	v_mov_b32_e32 v37, v24
	v_pk_mul_f32 v[36:37], v[36:37], s[18:19] op_sel_hi:[1,0]
	v_cvt_pk_fp8_f32 v34, v48, v46
	v_mul_f32_e32 v24, 0xbfb8aa3b, v36
	v_exp_f32_e32 v24, v24
	v_add_u32_e32 v32, 0x90, v124
	v_ashrrev_i32_e32 v33, 31, v32
	v_cvt_pk_fp8_f32 v34, v44, v40 op_sel:[0,0,1]
	v_add_f32_e32 v24, 1.0, v24
	v_rcp_f32_e32 v28, v24
	v_mov_b32_e32 v24, v29
	v_pk_mul_f32 v[24:25], v[24:25], s[18:19] op_sel_hi:[1,0]
	v_lshlrev_b64 v[32:33], 11, v[32:33]
	v_mul_f32_e32 v29, 0xbfb8aa3b, v24
	v_lshl_add_u64 v[32:33], s[16:17], 0, v[32:33]
	v_exp_f32_e32 v29, v29
	v_lshl_add_u64 v[32:33], v[32:33], 0, s[28:29]
	v_lshl_add_u64 v[32:33], v[32:33], 0, v[130:131]
	global_store_dwordx2 v[32:33], v[34:35], off
	v_mul_f32_e32 v32, v36, v37
	v_mul_f32_e32 v32, v28, v32
	v_add_f32_e32 v28, 1.0, v29
	v_rcp_f32_e32 v33, v28
	v_mov_b32_e32 v28, v30
	v_mov_b32_e32 v29, v26
	v_pk_mul_f32 v[28:29], v[28:29], s[18:19] op_sel_hi:[1,0]
	v_mul_f32_e32 v24, v24, v25
	v_mul_f32_e32 v26, 0xbfb8aa3b, v28
	v_exp_f32_e32 v26, v26
	v_mul_f32_e32 v30, v33, v24
	v_mul_f32_e32 v28, v28, v29
	v_add_f32_e32 v24, 1.0, v26
	v_mov_b32_e32 v26, v31
	v_rcp_f32_e32 v29, v24
	v_pk_mul_f32 v[24:25], v[26:27], s[18:19] op_sel_hi:[1,0]
	v_mov_b32_e32 v27, v16
	v_mul_f32_e32 v26, 0xbfb8aa3b, v24
	v_exp_f32_e32 v31, v26
	v_mov_b32_e32 v26, v20
	v_pk_mul_f32 v[26:27], v[26:27], s[18:19] op_sel_hi:[1,0]
	v_mul_f32_e32 v24, v24, v25
	v_mul_f32_e32 v16, 0xbfb8aa3b, v26
	v_exp_f32_e32 v16, v16
	v_add_f32_e32 v20, 1.0, v31
	v_rcp_f32_e32 v20, v20
	v_mul_f32_e32 v28, v29, v28
	v_add_f32_e32 v16, 1.0, v16
	v_rcp_f32_e32 v16, v16
	v_mul_f32_e32 v24, v20, v24
	v_mul_f32_e32 v20, v26, v27
	v_mul_f32_e32 v25, v16, v20
	v_mov_b32_e32 v16, v21
	v_pk_mul_f32 v[16:17], v[16:17], s[18:19] op_sel_hi:[1,0]
	v_mov_b32_e32 v21, v18
	v_mul_f32_e32 v20, 0xbfb8aa3b, v16
	v_exp_f32_e32 v26, v20
	v_mov_b32_e32 v20, v22
	v_pk_mul_f32 v[20:21], v[20:21], s[18:19] op_sel_hi:[1,0]
	v_mul_f32_e32 v22, v16, v17
	v_mul_f32_e32 v18, 0xbfb8aa3b, v20
	v_exp_f32_e32 v18, v18
	v_add_f32_e32 v16, 1.0, v26
	v_rcp_f32_e32 v26, v16
	v_add_f32_e32 v16, 1.0, v18
	v_mov_b32_e32 v18, v23
	v_rcp_f32_e32 v27, v16
	v_pk_mul_f32 v[16:17], v[18:19], s[18:19] op_sel_hi:[1,0]
	v_mul_f32_e32 v19, v20, v21
	v_mul_f32_e32 v18, 0xbfb8aa3b, v16
	v_exp_f32_e32 v18, v18
	v_mul_f32_e32 v22, v26, v22
	v_mul_f32_e32 v20, v27, v19
	v_mov_b32_e32 v19, v129
	v_add_f32_e32 v18, 1.0, v18
	v_rcp_f32_e32 v21, v18
	v_cvt_pk_fp8_f32 v19, v25, v22
	v_mul_f32_e32 v16, v16, v17
	v_mov_b32_e32 v18, v129
	v_mul_f32_e32 v16, v21, v16
	v_cvt_pk_fp8_f32 v19, v20, v16 op_sel:[0,0,1]
	v_mov_b32_e32 v20, v12
	v_mov_b32_e32 v21, v8
	v_pk_mul_f32 v[20:21], v[20:21], s[18:19] op_sel_hi:[1,0]
	v_cvt_pk_fp8_f32 v18, v32, v30
	v_mul_f32_e32 v8, 0xbfb8aa3b, v20
	v_exp_f32_e32 v8, v8
	v_add_u32_e32 v16, 0xa0, v124
	v_ashrrev_i32_e32 v17, 31, v16
	v_cvt_pk_fp8_f32 v18, v28, v24 op_sel:[0,0,1]
	v_add_f32_e32 v8, 1.0, v8
	v_rcp_f32_e32 v12, v8
	v_mov_b32_e32 v8, v13
	v_pk_mul_f32 v[8:9], v[8:9], s[18:19] op_sel_hi:[1,0]
	v_lshlrev_b64 v[16:17], 11, v[16:17]
	v_mul_f32_e32 v13, 0xbfb8aa3b, v8
	v_lshl_add_u64 v[16:17], s[16:17], 0, v[16:17]
	v_exp_f32_e32 v13, v13
	v_lshl_add_u64 v[16:17], v[16:17], 0, s[28:29]
	v_lshl_add_u64 v[16:17], v[16:17], 0, v[130:131]
	global_store_dwordx2 v[16:17], v[18:19], off
	v_mul_f32_e32 v16, v20, v21
	v_mul_f32_e32 v16, v12, v16
	v_add_f32_e32 v12, 1.0, v13
	v_rcp_f32_e32 v17, v12
	v_mov_b32_e32 v12, v14
	v_mov_b32_e32 v13, v10
	v_pk_mul_f32 v[12:13], v[12:13], s[18:19] op_sel_hi:[1,0]
	v_mul_f32_e32 v8, v8, v9
	v_mul_f32_e32 v10, 0xbfb8aa3b, v12
	v_exp_f32_e32 v10, v10
	v_mul_f32_e32 v14, v17, v8
	v_mul_f32_e32 v12, v12, v13
	v_add_f32_e32 v8, 1.0, v10
	v_mov_b32_e32 v10, v15
	v_rcp_f32_e32 v13, v8
	v_pk_mul_f32 v[8:9], v[10:11], s[18:19] op_sel_hi:[1,0]
	v_mov_b32_e32 v11, v0
	v_mul_f32_e32 v10, 0xbfb8aa3b, v8
	v_exp_f32_e32 v15, v10
	v_mov_b32_e32 v10, v4
	v_pk_mul_f32 v[10:11], v[10:11], s[18:19] op_sel_hi:[1,0]
	v_mul_f32_e32 v8, v8, v9
	v_mul_f32_e32 v0, 0xbfb8aa3b, v10
	v_exp_f32_e32 v0, v0
	v_add_f32_e32 v4, 1.0, v15
	v_rcp_f32_e32 v4, v4
	v_mul_f32_e32 v12, v13, v12
	v_add_f32_e32 v0, 1.0, v0
	v_rcp_f32_e32 v0, v0
	v_mul_f32_e32 v8, v4, v8
	v_mul_f32_e32 v4, v10, v11
	v_mul_f32_e32 v9, v0, v4
	v_mov_b32_e32 v0, v5
	v_pk_mul_f32 v[0:1], v[0:1], s[18:19] op_sel_hi:[1,0]
	v_mov_b32_e32 v5, v2
	v_mul_f32_e32 v4, 0xbfb8aa3b, v0
	v_exp_f32_e32 v10, v4
	v_mov_b32_e32 v4, v6
	v_pk_mul_f32 v[4:5], v[4:5], s[18:19] op_sel_hi:[1,0]
	v_mul_f32_e32 v6, v0, v1
	v_mul_f32_e32 v2, 0xbfb8aa3b, v4
	v_exp_f32_e32 v2, v2
	v_add_f32_e32 v0, 1.0, v10
	v_rcp_f32_e32 v10, v0
	v_add_f32_e32 v0, 1.0, v2
	v_mov_b32_e32 v2, v7
	v_rcp_f32_e32 v11, v0
	v_pk_mul_f32 v[0:1], v[2:3], s[18:19] op_sel_hi:[1,0]
	v_mul_f32_e32 v3, v4, v5
	v_mul_f32_e32 v2, 0xbfb8aa3b, v0
	v_exp_f32_e32 v2, v2
	v_mul_f32_e32 v6, v10, v6
	v_mul_f32_e32 v4, v11, v3
	v_mov_b32_e32 v3, v129
	v_add_f32_e32 v2, 1.0, v2
	v_rcp_f32_e32 v5, v2
	v_cvt_pk_fp8_f32 v3, v9, v6
	v_mov_b32_e32 v2, v129
	v_cvt_pk_fp8_f32 v2, v16, v14
	v_mul_f32_e32 v0, v0, v1
	v_mul_f32_e32 v0, v5, v0
	v_cvt_pk_fp8_f32 v3, v4, v0 op_sel:[0,0,1]
	v_add_u32_e32 v0, 0xb0, v124
	v_ashrrev_i32_e32 v1, 31, v0
	v_cvt_pk_fp8_f32 v2, v12, v8 op_sel:[0,0,1]
	v_lshlrev_b64 v[0:1], 11, v[0:1]
	v_lshl_add_u64 v[0:1], s[16:17], 0, v[0:1]
	v_lshl_add_u64 v[0:1], v[0:1], 0, s[28:29]
	v_lshl_add_u64 v[0:1], v[0:1], 0, v[130:131]
	global_store_dwordx2 v[0:1], v[2:3], off
	s_cbranch_vccnz .LBB0_1676
	s_andn2_b64 vcc, exec, s[10:11]
	s_cbranch_vccnz .LBB0_1675
	s_barrier
	s_branch .LBB0_1675

.LBB0_1741:
	s_mov_b32 s101, 0
	s_cmp_lt_i32 s56, 11
	s_cselect_b64 s[6:7], -1, 0
	s_and_b64 s[6:7], s[6:7], s[8:9]
	s_andn2_b64 vcc, exec, s[6:7]
	s_cbranch_vccnz .LBB0_1758
	s_waitcnt vmcnt(0)
	v_mbcnt_hi_u32_b32 v134, -1, v254
	v_mov_b32_e32 v0, v134
	s_cmpk_gt_i32 s92, 0x2ff
	s_cbranch_scc1 .LBB0_1758
	s_lshl_b32 s3, s33, 10
	v_lshl_add_u32 v1, v0, 4, s3
	v_add_u32_e32 v2, 0x2000, v1
	v_ashrrev_i32_e32 v3, 31, v2
	v_lshrrev_b32_e32 v3, 22, v3
	v_add_u32_e32 v3, v2, v3
	v_ashrrev_i32_e32 v3, 10, v3
	v_mul_i32_i24_e32 v5, 0x400, v3
	v_sub_u32_e32 v2, v2, v5
	v_lshrrev_b32_e32 v5, 4, v2
	v_bitop3_b32 v2, v5, v2, 32 bitop3:0x6c
	v_ashrrev_i32_e32 v5, 31, v2
	v_lshrrev_b32_e32 v5, 26, v5
	v_add_u32_e32 v5, v2, v5
	v_ashrrev_i32_e32 v6, 6, v5
	v_and_b32_e32 v5, 0xffc0, v5
	v_sub_u32_e32 v2, v2, v5
	v_lshrrev_b16_e32 v5, 7, v2
	v_lshlrev_b32_e32 v4, 5, v3
	v_and_b32_e32 v5, 1, v5
	v_lshlrev_b32_e32 v3, 3, v3
	v_add_u16_e32 v2, v2, v5
	v_mov_b32_e32 v5, 1
	v_and_b32_e32 v3, -16, v3
	v_and_b32_e32 v4, 32, v4
	v_ashrrev_i16_sdwa v2, v5, sext(v2) dst_sel:DWORD dst_unused:UNUSED_PAD src0_sel:DWORD src1_sel:BYTE_0
	v_add_u32_e32 v3, v6, v3
	v_add_u32_sdwa v2, v4, sext(v2) dst_sel:DWORD dst_unused:UNUSED_PAD src0_sel:DWORD src1_sel:WORD_0
	v_and_b32_e32 v4, 3, v6
	s_mov_b32 s8, 0xfffffe0
	v_lshrrev_b32_e32 v6, 2, v3
	v_lshlrev_b32_e32 v7, 1, v3
	v_and_or_b32 v4, v3, s8, v4
	v_and_b32_e32 v6, 4, v6
	v_and_b32_e32 v7, 24, v7
	v_or3_b32 v4, v4, v6, v7
	v_ashrrev_i32_e32 v6, 31, v1
	v_lshrrev_b32_e32 v6, 22, v6
	v_add_u32_e32 v6, v1, v6
	v_ashrrev_i32_e32 v6, 10, v6
	v_mul_i32_i24_e32 v8, 0x400, v6
	v_sub_u32_e32 v1, v1, v8
	v_lshrrev_b32_e32 v8, 4, v1
	v_bitop3_b32 v1, v8, v1, 32 bitop3:0x6c
	v_ashrrev_i32_e32 v8, 31, v1
	v_lshrrev_b32_e32 v8, 26, v8
	v_add_u32_e32 v8, v1, v8
	v_ashrrev_i32_e32 v9, 6, v8
	v_and_b32_e32 v8, 0xc0, v8
	v_sub_u32_e32 v1, v1, v8
	v_ashrrev_i16_sdwa v1, v5, sext(v1) dst_sel:DWORD dst_unused:UNUSED_PAD src0_sel:DWORD src1_sel:BYTE_0
	v_lshlrev_b32_e32 v5, 3, v6
	v_and_b32_e32 v5, -16, v5
	v_lshlrev_b32_e32 v7, 5, v6
	v_add_u32_e32 v5, v9, v5
	v_and_b32_e32 v6, 3, v9
	v_and_or_b32 v6, v5, s8, v6
	s_mul_hi_i32 s8, s92, 0x2aaaaaab
	s_lshr_b32 s9, s8, 31
	s_ashr_i32 s8, s8, 3
	s_add_i32 s8, s8, s9
	s_mul_i32 s9, s8, 48
	s_sub_i32 s9, s92, s9
	s_bfe_i32 s10, s9, 0x80000
	s_mul_i32 s10, s10, 43
	s_bfe_u32 s11, s10, 0x1000f
	s_bfe_u32 s10, s10, 0x80008
	s_add_i32 s14, s10, s11
	s_load_dwordx2 s[16:17], s[0:1], 0xf0
	s_mul_i32 s11, s14, 6
	s_sub_i32 s9, s9, s11
	s_mul_i32 s10, s8, 6
	s_sext_i32_i8 s9, s9
	s_lshr_b32 s12, s90, 8
	s_add_i32 s26, s10, s9
	s_waitcnt lgkmcnt(0)
	s_add_u32 s36, s16, 0x62358000
	s_addc_u32 s37, s17, 0
	s_ashr_i32 s27, s26, 31
	s_lshl_b64 s[10:11], s[26:27], 19
	s_add_u32 s28, s36, s10
	s_addc_u32 s29, s37, s11
	v_and_b32_e32 v7, 32, v7
	s_add_u32 s38, s16, 0x233d8000
	v_add_u32_sdwa v1, v7, sext(v1) dst_sel:DWORD dst_unused:UNUSED_PAD src0_sel:DWORD src1_sel:WORD_0
	v_lshrrev_b32_e32 v7, 2, v5
	v_lshlrev_b32_e32 v8, 1, v5
	s_addc_u32 s39, s17, 0
	s_ashr_i32 s9, s8, 31
	s_bfe_i64 s[10:11], s[14:15], 0x80000
	v_lshlrev_b32_e32 v5, 11, v5
	v_and_b32_e32 v7, 4, v7
	v_and_b32_e32 v8, 24, v8
	s_lshl_b64 s[8:9], s[8:9], 22
	s_lshl_b64 s[10:11], s[10:11], 12
	v_lshl_add_u32 v135, v1, 1, v5
	v_lshlrev_b32_e32 v1, 12, v1
	v_or3_b32 v6, v6, v7, v8
	s_add_u32 s8, s38, s8
	v_and_b32_e32 v1, 0xffff8000, v1
	s_addc_u32 s9, s39, s9
	v_lshl_add_u32 v137, v6, 4, v1
	v_lshlrev_b32_e32 v1, 12, v2
	s_add_u32 s30, s8, s10
	v_and_b32_e32 v1, 0xffff8000, v1
	s_addc_u32 s31, s9, s11
	v_lshlrev_b32_e32 v3, 11, v3
	v_lshl_add_u32 v138, v4, 4, v1
	s_add_i32 s40, s3, 0
	v_lshl_add_u32 v136, v2, 1, v3
	v_mov_b32_e32 v1, v137
	v_mov_b32_e32 v2, v138
	s_add_i32 m0, s40, 0x10000
	v_mov_b32_e32 v128, v137
	global_load_lds_dwordx4 v1, s[30:31]
	s_add_i32 m0, s40, 0x12000
	v_mov_b32_e32 v129, 0
	global_load_lds_dwordx4 v2, s[30:31]
	v_mov_b32_e32 v2, v138
	s_mov_b64 s[8:9], 0x800
	v_lshl_add_u64 v[4:5], s[30:31], 0, v[128:129]
	v_mov_b32_e32 v3, v129
	v_lshl_add_u64 v[4:5], v[4:5], 0, s[8:9]
	s_add_i32 m0, s40, 0x14000
	v_lshl_add_u64 v[2:3], s[30:31], 0, v[2:3]
	global_load_lds_dwordx4 v[4:5], off
	v_lshl_add_u64 v[2:3], v[2:3], 0, s[8:9]
	s_add_i32 m0, s40, 0x16000
	s_add_i32 s41, s40, 0x2000
	global_load_lds_dwordx4 v[2:3], off
	v_mov_b32_e32 v1, v136
	v_mov_b32_e32 v2, v135
	s_mov_b32 m0, s40
	s_add_u32 s10, s28, 0x40000
	s_addc_u32 s11, s29, 0
	global_load_lds_dwordx4 v2, s[28:29]
	s_mov_b32 m0, s41
	s_add_i32 s42, s40, 0x4000
	global_load_lds_dwordx4 v1, s[28:29]
	v_mov_b32_e32 v1, v135
	v_mov_b32_e32 v2, v136
	s_mov_b32 m0, s42
	s_add_i32 s43, s40, 0x6000
	s_cmp_eq_u32 s12, 1
	global_load_lds_dwordx4 v1, s[10:11]
	s_mov_b32 m0, s43
	s_nop 0
	global_load_lds_dwordx4 v2, s[10:11]
	s_cselect_b64 s[10:11], -1, 0
	s_cmp_lg_u32 s12, 1
	s_cbranch_scc1 .LBB0_1745
	s_barrier

.LBB0_1751:
	ds_read_b128 v[144:147], v140
	ds_read_b128 v[148:151], v140 offset:1024
	ds_read_b128 v[152:155], v140 offset:2048
	ds_read_b128 v[156:159], v140 offset:3072
	ds_read_b128 v[160:163], v141
	ds_read_b128 v[164:167], v141 offset:1024
	ds_read_b128 v[168:171], v141 offset:2048
	ds_read_b128 v[172:175], v141 offset:3072
	s_add_u32 s30, s28, 0xfffc0080
	s_addc_u32 s31, s29, -1
	s_cmp_eq_u32 s49, 12
	s_cselect_b32 s31, s21, s31
	s_cselect_b32 s30, s20, s30
	s_cselect_b32 s35, s23, s48
	s_cselect_b32 s34, s22, s19
	v_mov_b32_e32 v128, v136
	v_mov_b32_e32 v130, v135
	s_add_i32 m0, s40, 0xc000
	ds_read_b128 v[176:179], v142
	ds_read_b128 v[180:183], v142 offset:1024
	ds_read_b128 v[184:187], v142 offset:2048
	ds_read_b128 v[188:191], v142 offset:3072
	ds_read_b128 v[192:195], v142 offset:4096
	ds_read_b128 v[196:199], v142 offset:5120
	ds_read_b128 v[200:203], v142 offset:6144
	ds_read_b128 v[204:207], v142 offset:7168
	s_nop 0
	global_load_lds_dwordx4 v130, s[28:29]
	s_add_i32 m0, s40, 0xe000
	s_nop 0
	global_load_lds_dwordx4 v128, s[28:29]
	s_and_b64 vcc, exec, s[14:15]
	s_cbranch_vccnz .Lmy_lw_9
	s_cmp_lg_u32 s101, 0
	s_cbranch_scc1 .Lmy_rx_5
	s_waitcnt vmcnt(8)
	s_branch .Lmy_ry_5

.Lmy_ry_5:
.Lmy_lw_9:
	s_waitcnt lgkmcnt(0)
	s_barrier
	s_setprio 1
	s_waitcnt lgkmcnt(0)
	v_mfma_scale_f32_16x16x128_f8f6f4 v[124:127], v[144:151], v[176:183], v[124:127], v143, v143 op_sel_hi:[0,0,0]
	v_mfma_scale_f32_16x16x128_f8f6f4 v[120:123], v[152:159], v[176:183], v[120:123], v143, v143 op_sel_hi:[0,0,0]
	v_mfma_scale_f32_16x16x128_f8f6f4 v[112:115], v[144:151], v[184:191], v[112:115], v143, v143 op_sel_hi:[0,0,0]
	v_mfma_scale_f32_16x16x128_f8f6f4 v[104:107], v[152:159], v[184:191], v[104:107], v143, v143 op_sel_hi:[0,0,0]
	v_mfma_scale_f32_16x16x128_f8f6f4 v[96:99], v[144:151], v[192:199], v[96:99], v143, v143 op_sel_hi:[0,0,0]
	v_mfma_scale_f32_16x16x128_f8f6f4 v[130:133], v[152:159], v[192:199], v[88:91], v143, v143 op_sel_hi:[0,0,0]
	v_mfma_scale_f32_16x16x128_f8f6f4 v[208:211], v[144:151], v[200:207], v[80:83], v143, v143 op_sel_hi:[0,0,0]
	v_mfma_scale_f32_16x16x128_f8f6f4 v[212:215], v[152:159], v[200:207], v[72:75], v143, v143 op_sel_hi:[0,0,0]
	s_setprio 0
	s_setprio 1
	v_mfma_scale_f32_16x16x128_f8f6f4 v[116:119], v[160:167], v[176:183], v[116:119], v143, v143 op_sel_hi:[0,0,0]
	v_mfma_scale_f32_16x16x128_f8f6f4 v[108:111], v[168:175], v[176:183], v[108:111], v143, v143 op_sel_hi:[0,0,0]
	v_mfma_scale_f32_16x16x128_f8f6f4 v[100:103], v[160:167], v[184:191], v[100:103], v143, v143 op_sel_hi:[0,0,0]
	v_mfma_scale_f32_16x16x128_f8f6f4 v[176:179], v[168:175], v[184:191], v[92:95], v143, v143 op_sel_hi:[0,0,0]
	v_mfma_scale_f32_16x16x128_f8f6f4 v[180:183], v[160:167], v[192:199], v[84:87], v143, v143 op_sel_hi:[0,0,0]
	v_mfma_scale_f32_16x16x128_f8f6f4 v[184:187], v[168:175], v[192:199], v[76:79], v143, v143 op_sel_hi:[0,0,0]
	v_mfma_scale_f32_16x16x128_f8f6f4 v[188:191], v[160:167], v[200:207], v[68:71], v143, v143 op_sel_hi:[0,0,0]
	v_mfma_scale_f32_16x16x128_f8f6f4 v[192:195], v[168:175], v[200:207], v[64:67], v143, v143 op_sel_hi:[0,0,0]
	s_setprio 0
	s_cmp_lg_u32 s101, 0
	s_cbranch_scc1 .Lmy_rx_6
	s_waitcnt vmcnt(8)
	s_branch .Lmy_ry_6

.Lmy_ry_6:
	s_barrier
	s_add_i32 s63, s53, s3
	v_mov_b32_e32 v128, v138
	v_mov_b32_e32 v196, v137
	s_mov_b32 m0, s63
	s_nop 0
	ds_read_b128 v[64:67], v142 offset:16384
	ds_read_b128 v[68:71], v142 offset:17408
	ds_read_b128 v[72:75], v142 offset:18432
	ds_read_b128 v[76:79], v142 offset:19456
	ds_read_b128 v[80:83], v142 offset:20480
	ds_read_b128 v[84:87], v142 offset:21504
	ds_read_b128 v[88:91], v142 offset:22528
	ds_read_b128 v[92:95], v142 offset:23552
	v_mov_b32_e32 v197, v129
	global_load_lds_dwordx4 v196, s[34:35]
	s_add_i32 m0, s63, 0x2000
	v_mov_b32_e32 v196, v138
	global_load_lds_dwordx4 v128, s[34:35]
	v_mov_b32_e32 v128, v137
	s_add_i32 s63, s54, s3
	v_lshl_add_u64 v[198:199], s[34:35], 0, v[128:129]
	v_lshl_add_u64 v[198:199], v[198:199], 0, s[8:9]
	s_mov_b32 m0, s63
	v_lshl_add_u64 v[196:197], s[34:35], 0, v[196:197]
	global_load_lds_dwordx4 v[198:199], off
	v_lshl_add_u64 v[196:197], v[196:197], 0, s[8:9]
	s_add_i32 m0, s63, 0x2000
	v_mov_b32_e32 v128, v136
	global_load_lds_dwordx4 v[196:197], off
	v_mov_b32_e32 v196, v135
	s_mov_b32 m0, s40
	s_nop 0
	global_load_lds_dwordx4 v196, s[30:31]
	s_mov_b32 m0, s41
	s_nop 0
	global_load_lds_dwordx4 v128, s[30:31]
	s_and_b64 vcc, exec, s[14:15]
	s_cbranch_vccnz .Lmy_lw_10
	s_cmp_lg_u32 s101, 0
	s_cbranch_scc1 .Lmy_rx_7
	s_waitcnt vmcnt(8)
	s_branch .Lmy_ry_7

.Lmy_ry_7:
.Lmy_lw_10:
	s_waitcnt lgkmcnt(0)
	s_barrier
	s_setprio 1
	s_waitcnt lgkmcnt(0)
	v_mfma_scale_f32_16x16x128_f8f6f4 v[60:63], v[144:151], v[64:71], v[60:63], v143, v143 op_sel_hi:[0,0,0]
	v_mfma_scale_f32_16x16x128_f8f6f4 v[56:59], v[152:159], v[64:71], v[56:59], v143, v143 op_sel_hi:[0,0,0]
	v_mfma_scale_f32_16x16x128_f8f6f4 v[48:51], v[144:151], v[72:79], v[48:51], v143, v143 op_sel_hi:[0,0,0]
	v_mfma_scale_f32_16x16x128_f8f6f4 v[196:199], v[152:159], v[72:79], v[40:43], v143, v143 op_sel_hi:[0,0,0]
	v_mfma_scale_f32_16x16x128_f8f6f4 v[200:203], v[144:151], v[80:87], v[32:35], v143, v143 op_sel_hi:[0,0,0]
	v_mfma_scale_f32_16x16x128_f8f6f4 v[204:207], v[152:159], v[80:87], v[24:27], v143, v143 op_sel_hi:[0,0,0]
	v_mfma_scale_f32_16x16x128_f8f6f4 v[216:219], v[144:151], v[88:95], v[16:19], v143, v143 op_sel_hi:[0,0,0]
	v_mfma_scale_f32_16x16x128_f8f6f4 v[220:223], v[152:159], v[88:95], v[8:11], v143, v143 op_sel_hi:[0,0,0]
	s_setprio 0
	s_setprio 1
	v_mfma_scale_f32_16x16x128_f8f6f4 v[52:55], v[160:167], v[64:71], v[52:55], v143, v143 op_sel_hi:[0,0,0]
	v_mfma_scale_f32_16x16x128_f8f6f4 v[224:227], v[168:175], v[64:71], v[44:47], v143, v143 op_sel_hi:[0,0,0]
	v_mfma_scale_f32_16x16x128_f8f6f4 v[228:231], v[160:167], v[72:79], v[36:39], v143, v143 op_sel_hi:[0,0,0]
	v_mfma_scale_f32_16x16x128_f8f6f4 v[232:235], v[168:175], v[72:79], v[28:31], v143, v143 op_sel_hi:[0,0,0]
	v_mfma_scale_f32_16x16x128_f8f6f4 v[236:239], v[160:167], v[80:87], v[20:23], v143, v143 op_sel_hi:[0,0,0]
	v_mfma_scale_f32_16x16x128_f8f6f4 v[240:243], v[168:175], v[80:87], v[12:15], v143, v143 op_sel_hi:[0,0,0]
	v_mfma_scale_f32_16x16x128_f8f6f4 v[244:247], v[160:167], v[88:95], v[4:7], v143, v143 op_sel_hi:[0,0,0]
	v_mfma_scale_f32_16x16x128_f8f6f4 v[248:251], v[168:175], v[88:95], v[0:3], v143, v143 op_sel_hi:[0,0,0]
	s_setprio 0
	s_cmp_lg_u32 s101, 0
	s_cbranch_scc1 .Lmy_rx_8
	s_waitcnt vmcnt(8)
	s_branch .Lmy_ry_8

.Lmy_ry_8:
	s_mov_b32 s101, 0
	s_barrier
	s_add_i32 s63, 0, 0x18000
	s_add_i32 s66, 0, 0x1c000
	s_nop 0
	v_add_u32_e32 v12, s63, v139
	v_add_u32_e32 v16, s66, v139
	ds_read_b128 v[0:3], v12
	ds_read_b128 v[4:7], v12 offset:1024
	ds_read_b128 v[8:11], v12 offset:2048
	ds_read_b128 v[12:15], v12 offset:3072
	ds_read_b128 v[144:147], v16
	ds_read_b128 v[148:151], v16 offset:1024
	ds_read_b128 v[152:155], v16 offset:2048
	ds_read_b128 v[156:159], v16 offset:3072
	s_add_u32 s64, s30, 0x40000
	v_mov_b32_e32 v64, v136
	v_mov_b32_e32 v65, v135
	s_addc_u32 s65, s31, 0
	s_mov_b32 m0, s42
	ds_read_b128 v[16:19], v142 offset:32768
	ds_read_b128 v[20:23], v142 offset:33792
	ds_read_b128 v[24:27], v142 offset:34816
	ds_read_b128 v[28:31], v142 offset:35840
	ds_read_b128 v[32:35], v142 offset:36864
	ds_read_b128 v[36:39], v142 offset:37888
	ds_read_b128 v[40:43], v142 offset:38912
	ds_read_b128 v[44:47], v142 offset:39936
	s_nop 0
	global_load_lds_dwordx4 v65, s[64:65]
	s_mov_b32 m0, s43
	s_nop 0
	global_load_lds_dwordx4 v64, s[64:65]
	s_and_b64 vcc, exec, s[14:15]
	s_cbranch_vccnz .Lmy_lw_11
	s_waitcnt vmcnt(8)

.LBB0_1754:
	s_mov_b32 s101, 1
	v_mov_b32_e32 v128, v134
	s_lshl_b32 s19, s26, 8
	s_add_i32 s19, s19, s44
	v_ashrrev_i32_e32 v130, 1, v128
	v_and_or_b32 v132, v128, 15, s19
	v_mul_f32_e32 v124, 0x3e000000, v124
	v_mul_f32_e32 v125, 0x3e000000, v125
	v_mul_f32_e32 v128, 0x3e000000, v120
	v_mul_f32_e32 v131, 0x3e000000, v121
	v_mov_b32_e32 v120, v129
	v_mov_b32_e32 v121, v129
	v_cvt_pk_fp8_f32 v120, v124, v125
	v_cvt_pk_fp8_f32 v121, v128, v131
	v_mul_f32_e32 v116, 0x3e000000, v116
	v_mul_f32_e32 v117, 0x3e000000, v117
	v_mul_f32_e32 v124, 0x3e000000, v108
	v_mul_f32_e32 v125, 0x3e000000, v109
	v_mov_b32_e32 v108, v129
	v_mov_b32_e32 v109, v129
	v_cvt_pk_fp8_f32 v108, v116, v117
	v_cvt_pk_fp8_f32 v109, v124, v125
	v_ashrrev_i32_e32 v133, 31, v132
	v_mul_f32_e32 v126, 0x3e000000, v126
	v_mul_f32_e32 v127, 0x3e000000, v127
	v_mul_f32_e32 v122, 0x3e000000, v122
	v_mul_f32_e32 v123, 0x3e000000, v123
	v_and_b32_e32 v130, -8, v130
	s_lshl_b32 s26, s27, 8
	v_lshlrev_b64 v[144:145], 11, v[132:133]
	v_cvt_pk_fp8_f32 v120, v126, v127 op_sel:[0,0,1]
	v_cvt_pk_fp8_f32 v121, v122, v123 op_sel:[0,0,1]
	v_mul_f32_e32 v118, 0x3e000000, v118
	v_mul_f32_e32 v119, 0x3e000000, v119
	v_mul_f32_e32 v110, 0x3e000000, v110
	v_mul_f32_e32 v111, 0x3e000000, v111
	v_add_u32_e32 v130, s45, v130
	s_ashr_i32 s27, s26, 31
	v_lshl_add_u64 v[122:123], s[16:17], 0, v[144:145]
	v_cvt_pk_fp8_f32 v108, v118, v119 op_sel:[0,0,1]
	v_cvt_pk_fp8_f32 v109, v110, v111 op_sel:[0,0,1]
	v_lshl_add_u64 v[122:123], v[122:123], 0, s[26:27]
	v_ashrrev_i32_e32 v131, 31, v130
	v_lshl_add_u64 v[110:111], v[122:123], 0, v[130:131]
	global_store_dwordx2 v[110:111], v[120:121], off
	global_store_dwordx2 v[110:111], v[108:109], off offset:128
	v_mul_f32_e32 v110, 0x3e000000, v112
	v_mul_f32_e32 v111, 0x3e000000, v113
	v_mul_f32_e32 v112, 0x3e000000, v114
	v_mul_f32_e32 v113, 0x3e000000, v115
	v_mul_f32_e32 v114, 0x3e000000, v104
	v_mul_f32_e32 v115, 0x3e000000, v105
	v_mov_b32_e32 v105, v129
	v_cvt_pk_fp8_f32 v105, v114, v115
	v_or_b32_e32 v108, 16, v132
	v_ashrrev_i32_e32 v109, 31, v108
	v_lshlrev_b64 v[108:109], 11, v[108:109]
	v_mov_b32_e32 v104, v129
	v_mul_f32_e32 v106, 0x3e000000, v106
	v_mul_f32_e32 v107, 0x3e000000, v107
	v_cvt_pk_fp8_f32 v104, v110, v111
	v_cvt_pk_fp8_f32 v105, v106, v107 op_sel:[0,0,1]
	v_lshl_add_u64 v[106:107], s[16:17], 0, v[108:109]
	v_mul_f32_e32 v100, 0x3e000000, v100
	v_mul_f32_e32 v101, 0x3e000000, v101
	v_mul_f32_e32 v108, 0x3e000000, v92
	v_mul_f32_e32 v109, 0x3e000000, v93
	v_mov_b32_e32 v92, v129
	v_mov_b32_e32 v93, v129
	v_cvt_pk_fp8_f32 v92, v100, v101
	v_cvt_pk_fp8_f32 v93, v108, v109
	v_cvt_pk_fp8_f32 v104, v112, v113 op_sel:[0,0,1]
	v_mul_f32_e32 v102, 0x3e000000, v102
	v_mul_f32_e32 v103, 0x3e000000, v103
	v_mul_f32_e32 v94, 0x3e000000, v94
	v_mul_f32_e32 v95, 0x3e000000, v95
	v_cvt_pk_fp8_f32 v92, v102, v103 op_sel:[0,0,1]
	v_cvt_pk_fp8_f32 v93, v94, v95 op_sel:[0,0,1]
	v_lshl_add_u64 v[94:95], v[106:107], 0, s[26:27]
	v_lshl_add_u64 v[94:95], v[94:95], 0, v[130:131]
	global_store_dwordx2 v[94:95], v[104:105], off
	global_store_dwordx2 v[94:95], v[92:93], off offset:128
	v_mul_f32_e32 v94, 0x3e000000, v96
	v_mul_f32_e32 v95, 0x3e000000, v97
	v_mul_f32_e32 v96, 0x3e000000, v98
	v_mul_f32_e32 v97, 0x3e000000, v99
	v_mul_f32_e32 v98, 0x3e000000, v88
	v_mul_f32_e32 v99, 0x3e000000, v89
	v_mov_b32_e32 v89, v129
	v_cvt_pk_fp8_f32 v89, v98, v99
	v_or_b32_e32 v92, 32, v132
	v_ashrrev_i32_e32 v93, 31, v92
	v_lshlrev_b64 v[92:93], 11, v[92:93]
	v_mov_b32_e32 v88, v129
	v_mul_f32_e32 v90, 0x3e000000, v90
	v_mul_f32_e32 v91, 0x3e000000, v91
	v_cvt_pk_fp8_f32 v88, v94, v95
	v_cvt_pk_fp8_f32 v89, v90, v91 op_sel:[0,0,1]
	v_lshl_add_u64 v[90:91], s[16:17], 0, v[92:93]
	v_mul_f32_e32 v84, 0x3e000000, v84
	v_mul_f32_e32 v85, 0x3e000000, v85
	v_mul_f32_e32 v92, 0x3e000000, v76
	v_mul_f32_e32 v93, 0x3e000000, v77
	v_mov_b32_e32 v76, v129
	v_mov_b32_e32 v77, v129
	v_cvt_pk_fp8_f32 v76, v84, v85
	v_cvt_pk_fp8_f32 v77, v92, v93
	v_cvt_pk_fp8_f32 v88, v96, v97 op_sel:[0,0,1]
	v_mul_f32_e32 v86, 0x3e000000, v86
	v_mul_f32_e32 v87, 0x3e000000, v87
	v_mul_f32_e32 v78, 0x3e000000, v78
	v_mul_f32_e32 v79, 0x3e000000, v79
	v_cvt_pk_fp8_f32 v76, v86, v87 op_sel:[0,0,1]
	v_cvt_pk_fp8_f32 v77, v78, v79 op_sel:[0,0,1]
	v_lshl_add_u64 v[78:79], v[90:91], 0, s[26:27]
	v_lshl_add_u64 v[78:79], v[78:79], 0, v[130:131]
	global_store_dwordx2 v[78:79], v[88:89], off
	global_store_dwordx2 v[78:79], v[76:77], off offset:128
	v_mul_f32_e32 v78, 0x3e000000, v80
	v_mul_f32_e32 v79, 0x3e000000, v81
	v_mul_f32_e32 v80, 0x3e000000, v82
	v_mul_f32_e32 v81, 0x3e000000, v83
	v_mul_f32_e32 v82, 0x3e000000, v72
	v_mul_f32_e32 v83, 0x3e000000, v73
	v_mov_b32_e32 v73, v129
	v_cvt_pk_fp8_f32 v73, v82, v83
	v_or_b32_e32 v76, 48, v132
	v_ashrrev_i32_e32 v77, 31, v76
	v_lshlrev_b64 v[76:77], 11, v[76:77]
	v_mov_b32_e32 v72, v129
	v_mul_f32_e32 v74, 0x3e000000, v74
	v_mul_f32_e32 v75, 0x3e000000, v75
	v_cvt_pk_fp8_f32 v72, v78, v79
	v_cvt_pk_fp8_f32 v73, v74, v75 op_sel:[0,0,1]
	v_lshl_add_u64 v[74:75], s[16:17], 0, v[76:77]
	v_mul_f32_e32 v68, 0x3e000000, v68
	v_mul_f32_e32 v69, 0x3e000000, v69
	v_mul_f32_e32 v76, 0x3e000000, v64
	v_mul_f32_e32 v77, 0x3e000000, v65
	v_mov_b32_e32 v64, v129
	v_mov_b32_e32 v65, v129
	v_cvt_pk_fp8_f32 v64, v68, v69
	v_cvt_pk_fp8_f32 v65, v76, v77
	v_cvt_pk_fp8_f32 v72, v80, v81 op_sel:[0,0,1]
	v_mul_f32_e32 v70, 0x3e000000, v70
	v_mul_f32_e32 v71, 0x3e000000, v71
	v_mul_f32_e32 v66, 0x3e000000, v66
	v_mul_f32_e32 v67, 0x3e000000, v67
	v_cvt_pk_fp8_f32 v64, v70, v71 op_sel:[0,0,1]
	v_cvt_pk_fp8_f32 v65, v66, v67 op_sel:[0,0,1]
	v_lshl_add_u64 v[66:67], v[74:75], 0, s[26:27]
	v_lshl_add_u64 v[66:67], v[66:67], 0, v[130:131]
	global_store_dwordx2 v[66:67], v[72:73], off
	global_store_dwordx2 v[66:67], v[64:65], off offset:128
	v_mul_f32_e32 v60, 0x3e000000, v60
	v_mul_f32_e32 v61, 0x3e000000, v61
	v_mul_f32_e32 v66, 0x3e000000, v56
	v_mul_f32_e32 v67, 0x3e000000, v57
	v_mov_b32_e32 v56, v129
	v_mov_b32_e32 v57, v129
	v_cvt_pk_fp8_f32 v56, v60, v61
	v_cvt_pk_fp8_f32 v57, v66, v67
	v_mul_f32_e32 v52, 0x3e000000, v52
	v_mul_f32_e32 v53, 0x3e000000, v53
	v_mul_f32_e32 v60, 0x3e000000, v44
	v_mul_f32_e32 v61, 0x3e000000, v45
	v_mov_b32_e32 v44, v129
	v_mov_b32_e32 v45, v129
	v_cvt_pk_fp8_f32 v44, v52, v53
	v_cvt_pk_fp8_f32 v45, v60, v61
	v_add_u32_e32 v64, 0x80, v132
	v_ashrrev_i32_e32 v65, 31, v64
	v_mul_f32_e32 v62, 0x3e000000, v62
	v_mul_f32_e32 v63, 0x3e000000, v63
	v_mul_f32_e32 v58, 0x3e000000, v58
	v_mul_f32_e32 v59, 0x3e000000, v59
	v_lshlrev_b64 v[64:65], 11, v[64:65]
	v_cvt_pk_fp8_f32 v56, v62, v63 op_sel:[0,0,1]
	v_cvt_pk_fp8_f32 v57, v58, v59 op_sel:[0,0,1]
	v_mul_f32_e32 v54, 0x3e000000, v54
	v_mul_f32_e32 v55, 0x3e000000, v55
	v_mul_f32_e32 v46, 0x3e000000, v46
	v_mul_f32_e32 v47, 0x3e000000, v47
	v_lshl_add_u64 v[58:59], s[16:17], 0, v[64:65]
	v_cvt_pk_fp8_f32 v44, v54, v55 op_sel:[0,0,1]
	v_cvt_pk_fp8_f32 v45, v46, v47 op_sel:[0,0,1]
	v_lshl_add_u64 v[46:47], v[58:59], 0, s[26:27]
	v_lshl_add_u64 v[46:47], v[46:47], 0, v[130:131]
	global_store_dwordx2 v[46:47], v[56:57], off
	global_store_dwordx2 v[46:47], v[44:45], off offset:128
	v_mul_f32_e32 v46, 0x3e000000, v48
	v_mul_f32_e32 v47, 0x3e000000, v49
	v_mul_f32_e32 v48, 0x3e000000, v50
	v_mul_f32_e32 v49, 0x3e000000, v51
	v_mul_f32_e32 v50, 0x3e000000, v40
	v_mul_f32_e32 v51, 0x3e000000, v41
	v_mov_b32_e32 v41, v129
	v_cvt_pk_fp8_f32 v41, v50, v51
	v_add_u32_e32 v44, 0x90, v132
	v_ashrrev_i32_e32 v45, 31, v44
	v_lshlrev_b64 v[44:45], 11, v[44:45]
	v_mov_b32_e32 v40, v129
	v_mul_f32_e32 v42, 0x3e000000, v42
	v_mul_f32_e32 v43, 0x3e000000, v43
	v_cvt_pk_fp8_f32 v40, v46, v47
	v_cvt_pk_fp8_f32 v41, v42, v43 op_sel:[0,0,1]
	v_lshl_add_u64 v[42:43], s[16:17], 0, v[44:45]
	v_mul_f32_e32 v36, 0x3e000000, v36
	v_mul_f32_e32 v37, 0x3e000000, v37
	v_mul_f32_e32 v44, 0x3e000000, v28
	v_mul_f32_e32 v45, 0x3e000000, v29
	v_mov_b32_e32 v28, v129
	v_mov_b32_e32 v29, v129
	v_cvt_pk_fp8_f32 v28, v36, v37
	v_cvt_pk_fp8_f32 v29, v44, v45
	v_cvt_pk_fp8_f32 v40, v48, v49 op_sel:[0,0,1]
	v_mul_f32_e32 v38, 0x3e000000, v38
	v_mul_f32_e32 v39, 0x3e000000, v39
	v_mul_f32_e32 v30, 0x3e000000, v30
	v_mul_f32_e32 v31, 0x3e000000, v31
	v_cvt_pk_fp8_f32 v28, v38, v39 op_sel:[0,0,1]
	v_cvt_pk_fp8_f32 v29, v30, v31 op_sel:[0,0,1]
	v_lshl_add_u64 v[30:31], v[42:43], 0, s[26:27]
	v_lshl_add_u64 v[30:31], v[30:31], 0, v[130:131]
	global_store_dwordx2 v[30:31], v[40:41], off
	global_store_dwordx2 v[30:31], v[28:29], off offset:128
	v_mul_f32_e32 v30, 0x3e000000, v32
	v_mul_f32_e32 v31, 0x3e000000, v33
	v_mul_f32_e32 v32, 0x3e000000, v34
	v_mul_f32_e32 v33, 0x3e000000, v35
	v_mul_f32_e32 v34, 0x3e000000, v24
	v_mul_f32_e32 v35, 0x3e000000, v25
	v_mov_b32_e32 v25, v129
	v_cvt_pk_fp8_f32 v25, v34, v35
	v_add_u32_e32 v28, 0xa0, v132
	v_ashrrev_i32_e32 v29, 31, v28
	v_lshlrev_b64 v[28:29], 11, v[28:29]
	v_mov_b32_e32 v24, v129
	v_mul_f32_e32 v26, 0x3e000000, v26
	v_mul_f32_e32 v27, 0x3e000000, v27
	v_cvt_pk_fp8_f32 v24, v30, v31
	v_cvt_pk_fp8_f32 v25, v26, v27 op_sel:[0,0,1]
	v_lshl_add_u64 v[26:27], s[16:17], 0, v[28:29]
	v_mul_f32_e32 v20, 0x3e000000, v20
	v_mul_f32_e32 v21, 0x3e000000, v21
	v_mul_f32_e32 v28, 0x3e000000, v12
	v_mul_f32_e32 v29, 0x3e000000, v13
	v_mov_b32_e32 v12, v129
	v_mov_b32_e32 v13, v129
	v_cvt_pk_fp8_f32 v12, v20, v21
	v_cvt_pk_fp8_f32 v13, v28, v29
	v_cvt_pk_fp8_f32 v24, v32, v33 op_sel:[0,0,1]
	v_mul_f32_e32 v22, 0x3e000000, v22
	v_mul_f32_e32 v23, 0x3e000000, v23
	v_mul_f32_e32 v14, 0x3e000000, v14
	v_mul_f32_e32 v15, 0x3e000000, v15
	v_cvt_pk_fp8_f32 v12, v22, v23 op_sel:[0,0,1]
	v_cvt_pk_fp8_f32 v13, v14, v15 op_sel:[0,0,1]
	v_lshl_add_u64 v[14:15], v[26:27], 0, s[26:27]
	v_lshl_add_u64 v[14:15], v[14:15], 0, v[130:131]
	global_store_dwordx2 v[14:15], v[24:25], off
	global_store_dwordx2 v[14:15], v[12:13], off offset:128
	v_mul_f32_e32 v14, 0x3e000000, v16
	v_mul_f32_e32 v15, 0x3e000000, v17
	v_mul_f32_e32 v16, 0x3e000000, v18
	v_mul_f32_e32 v17, 0x3e000000, v19
	v_mul_f32_e32 v18, 0x3e000000, v8
	v_mul_f32_e32 v19, 0x3e000000, v9
	v_mov_b32_e32 v9, v129
	v_cvt_pk_fp8_f32 v9, v18, v19
	v_add_u32_e32 v12, 0xb0, v132
	v_ashrrev_i32_e32 v13, 31, v12
	v_lshlrev_b64 v[12:13], 11, v[12:13]
	v_mov_b32_e32 v8, v129
	v_mul_f32_e32 v10, 0x3e000000, v10
	v_mul_f32_e32 v11, 0x3e000000, v11
	v_cvt_pk_fp8_f32 v8, v14, v15
	v_cvt_pk_fp8_f32 v9, v10, v11 op_sel:[0,0,1]
	v_lshl_add_u64 v[10:11], s[16:17], 0, v[12:13]
	v_mul_f32_e32 v4, 0x3e000000, v4
	v_mul_f32_e32 v5, 0x3e000000, v5
	v_mul_f32_e32 v12, 0x3e000000, v0
	v_mul_f32_e32 v13, 0x3e000000, v1
	v_mov_b32_e32 v0, v129
	v_mov_b32_e32 v1, v129
	v_cvt_pk_fp8_f32 v0, v4, v5
	v_cvt_pk_fp8_f32 v1, v12, v13
	v_cvt_pk_fp8_f32 v8, v16, v17 op_sel:[0,0,1]
	v_mul_f32_e32 v6, 0x3e000000, v6
	v_mul_f32_e32 v7, 0x3e000000, v7
	v_mul_f32_e32 v2, 0x3e000000, v2
	v_mul_f32_e32 v3, 0x3e000000, v3
	v_cvt_pk_fp8_f32 v0, v6, v7 op_sel:[0,0,1]
	v_cvt_pk_fp8_f32 v1, v2, v3 op_sel:[0,0,1]
	v_lshl_add_u64 v[2:3], v[10:11], 0, s[26:27]
	v_lshl_add_u64 v[2:3], v[2:3], 0, v[130:131]
	s_andn2_b64 vcc, exec, s[24:25]
	s_mov_b64 s[24:25], -1
	global_store_dwordx2 v[2:3], v[8:9], off
	global_store_dwordx2 v[2:3], v[0:1], off offset:128
	s_cbranch_vccnz .LBB0_1747
	s_andn2_b64 vcc, exec, s[10:11]
	s_cbranch_vccnz .LBB0_1746
	s_barrier
	s_branch .LBB0_1746

.LBB0_2883:
	s_mov_b32 s101, 0
	s_cmp_lt_i32 s56, 18
	s_cselect_b64 s[8:9], -1, 0
	s_and_b64 s[6:7], s[8:9], s[6:7]
	s_andn2_b64 vcc, exec, s[6:7]
	s_cbranch_vccnz .LBB0_2900
	s_waitcnt vmcnt(0)
	v_mbcnt_hi_u32_b32 v132, -1, v254
	v_mov_b32_e32 v0, v132
	s_cmpk_gt_i32 s92, 0x5ff
	s_cbranch_scc1 .LBB0_2900
	s_lshl_b32 s3, s33, 10
	v_lshl_add_u32 v1, v0, 4, s3
	v_add_u32_e32 v2, 0x2000, v1
	v_ashrrev_i32_e32 v3, 31, v2
	v_lshrrev_b32_e32 v3, 22, v3
	v_add_u32_e32 v3, v2, v3
	v_ashrrev_i32_e32 v3, 10, v3
	v_mul_i32_i24_e32 v5, 0x400, v3
	v_sub_u32_e32 v2, v2, v5
	v_lshrrev_b32_e32 v5, 4, v2
	v_bitop3_b32 v2, v5, v2, 32 bitop3:0x6c
	v_ashrrev_i32_e32 v5, 31, v2
	v_lshrrev_b32_e32 v5, 26, v5
	v_add_u32_e32 v5, v2, v5
	v_ashrrev_i32_e32 v6, 6, v5
	v_and_b32_e32 v5, 0xffc0, v5
	v_sub_u32_e32 v2, v2, v5
	v_lshrrev_b16_e32 v5, 7, v2
	v_lshlrev_b32_e32 v4, 5, v3
	v_and_b32_e32 v5, 1, v5
	v_lshlrev_b32_e32 v3, 3, v3
	v_add_u16_e32 v2, v2, v5
	v_mov_b32_e32 v5, 1
	v_and_b32_e32 v3, -16, v3
	v_and_b32_e32 v4, 32, v4
	v_ashrrev_i16_sdwa v2, v5, sext(v2) dst_sel:DWORD dst_unused:UNUSED_PAD src0_sel:DWORD src1_sel:BYTE_0
	v_add_u32_e32 v3, v6, v3
	v_add_u32_sdwa v2, v4, sext(v2) dst_sel:DWORD dst_unused:UNUSED_PAD src0_sel:DWORD src1_sel:WORD_0
	v_and_b32_e32 v4, 3, v6
	s_mov_b32 s8, 0xfffffe0
	v_lshrrev_b32_e32 v6, 2, v3
	v_lshlrev_b32_e32 v7, 1, v3
	v_and_or_b32 v4, v3, s8, v4
	v_and_b32_e32 v6, 4, v6
	v_and_b32_e32 v7, 24, v7
	v_or3_b32 v4, v4, v6, v7
	v_ashrrev_i32_e32 v6, 31, v1
	v_lshrrev_b32_e32 v6, 22, v6
	v_add_u32_e32 v6, v1, v6
	v_ashrrev_i32_e32 v6, 10, v6
	v_mul_i32_i24_e32 v8, 0x400, v6
	v_sub_u32_e32 v1, v1, v8
	v_lshrrev_b32_e32 v8, 4, v1
	v_bitop3_b32 v1, v8, v1, 32 bitop3:0x6c
	v_ashrrev_i32_e32 v8, 31, v1
	v_lshrrev_b32_e32 v8, 26, v8
	v_add_u32_e32 v8, v1, v8
	v_ashrrev_i32_e32 v9, 6, v8
	v_and_b32_e32 v8, 0xc0, v8
	v_sub_u32_e32 v1, v1, v8
	v_ashrrev_i16_sdwa v1, v5, sext(v1) dst_sel:DWORD dst_unused:UNUSED_PAD src0_sel:DWORD src1_sel:BYTE_0
	v_lshlrev_b32_e32 v5, 3, v6
	v_and_b32_e32 v5, -16, v5
	v_lshlrev_b32_e32 v7, 5, v6
	v_add_u32_e32 v5, v9, v5
	v_and_b32_e32 v6, 3, v9
	v_and_or_b32 v6, v5, s8, v6
	s_mul_hi_i32 s8, s92, 0x2aaaaaab
	s_lshr_b32 s9, s8, 31
	s_ashr_i32 s8, s8, 4
	s_add_i32 s8, s8, s9
	s_mul_i32 s9, s8, 0x60
	s_sub_i32 s9, s92, s9
	s_mul_i32 s10, s9, 43
	s_bfe_u32 s11, s10, 0x1000f
	s_bfe_u32 s10, s10, 0x80008
	s_add_i32 s14, s10, s11
	s_load_dwordx2 s[16:17], s[0:1], 0xf0
	s_mul_i32 s11, s14, 6
	s_sub_i32 s9, s9, s11
	s_mul_i32 s10, s8, 6
	s_sext_i32_i8 s9, s9
	s_lshr_b32 s12, s90, 8
	s_add_i32 s28, s10, s9
	s_waitcnt lgkmcnt(0)
	s_add_u32 s19, s16, 0x5c358000
	s_addc_u32 s38, s17, 0
	s_ashr_i32 s29, s28, 31
	s_lshl_b64 s[10:11], s[28:29], 19
	s_add_u32 s30, s19, s10
	s_addc_u32 s31, s38, s11
	s_add_u32 s39, s16, 0x33d8000
	v_and_b32_e32 v7, 32, v7
	s_addc_u32 s40, s17, 0
	s_ashr_i32 s9, s8, 31
	s_bfe_i64 s[10:11], s[14:15], 0x80000
	v_add_u32_sdwa v1, v7, sext(v1) dst_sel:DWORD dst_unused:UNUSED_PAD src0_sel:DWORD src1_sel:WORD_0
	v_lshrrev_b32_e32 v7, 2, v5
	v_lshlrev_b32_e32 v8, 1, v5
	s_lshl_b64 s[8:9], s[8:9], 23
	s_lshl_b64 s[10:11], s[10:11], 12
	v_lshlrev_b32_e32 v5, 11, v5
	v_and_b32_e32 v7, 4, v7
	v_and_b32_e32 v8, 24, v8
	s_add_u32 s8, s39, s8
	v_lshl_add_u32 v133, v1, 1, v5
	v_lshlrev_b32_e32 v1, 13, v1
	v_or3_b32 v6, v6, v7, v8
	s_addc_u32 s9, s40, s9
	v_and_b32_e32 v1, 0xffff0000, v1
	s_add_u32 s8, s8, s10
	v_lshl_add_u32 v135, v6, 4, v1
	v_lshlrev_b32_e32 v1, 13, v2
	s_addc_u32 s9, s9, s11
	v_and_b32_e32 v1, 0xffff0000, v1
	s_add_u32 s34, s8, 0x8000000
	v_lshlrev_b32_e32 v3, 11, v3
	v_lshl_add_u32 v136, v4, 4, v1
	s_addc_u32 s35, s9, 0
	v_lshl_add_u32 v134, v2, 1, v3
	v_mov_b32_e32 v1, v136
	v_mov_b32_e32 v2, v135
	s_add_i32 s41, s3, 0
	s_add_i32 m0, s41, 0x10000
	v_mov_b32_e32 v128, v135
	global_load_lds_dwordx4 v2, s[34:35]
	s_add_i32 m0, s41, 0x12000
	v_mov_b32_e32 v2, v136
	v_mov_b32_e32 v129, 0
	global_load_lds_dwordx4 v1, s[34:35]
	s_mov_b64 s[8:9], 0x800
	v_lshl_add_u64 v[4:5], s[34:35], 0, v[128:129]
	v_mov_b32_e32 v3, v129
	v_lshl_add_u64 v[4:5], v[4:5], 0, s[8:9]
	s_add_i32 m0, s41, 0x14000
	v_lshl_add_u64 v[2:3], s[34:35], 0, v[2:3]
	global_load_lds_dwordx4 v[4:5], off
	v_lshl_add_u64 v[2:3], v[2:3], 0, s[8:9]
	s_add_i32 m0, s41, 0x16000
	s_add_i32 s42, s41, 0x2000
	global_load_lds_dwordx4 v[2:3], off
	v_mov_b32_e32 v1, v133
	v_mov_b32_e32 v2, v134
	s_mov_b32 m0, s41
	s_add_u32 s10, s30, 0x40000
	s_addc_u32 s11, s31, 0
	global_load_lds_dwordx4 v1, s[30:31]
	s_mov_b32 m0, s42
	s_add_i32 s43, s41, 0x4000
	global_load_lds_dwordx4 v2, s[30:31]
	v_mov_b32_e32 v1, v133
	v_mov_b32_e32 v2, v134
	s_mov_b32 m0, s43
	s_add_i32 s44, s41, 0x6000
	s_cmp_eq_u32 s12, 1
	global_load_lds_dwordx4 v1, s[10:11]
	s_mov_b32 m0, s44
	s_nop 0
	global_load_lds_dwordx4 v2, s[10:11]
	s_cselect_b64 s[10:11], -1, 0
	s_cmp_lg_u32 s12, 1
	s_cbranch_scc1 .LBB0_2887
	s_barrier

.LBB0_2893:
	ds_read_b128 v[142:145], v138
	ds_read_b128 v[146:149], v138 offset:1024
	ds_read_b128 v[150:153], v138 offset:2048
	ds_read_b128 v[154:157], v138 offset:3072
	ds_read_b128 v[158:161], v139
	ds_read_b128 v[162:165], v139 offset:1024
	ds_read_b128 v[166:169], v139 offset:2048
	ds_read_b128 v[170:173], v139 offset:3072
	s_add_u32 s34, s30, 0xfffc0080
	s_addc_u32 s35, s31, -1
	s_cmp_eq_u32 s54, 12
	s_cselect_b32 s35, s23, s35
	s_cselect_b32 s34, s22, s34
	s_cselect_b32 s37, s25, s53
	s_cselect_b32 s36, s24, s21
	v_mov_b32_e32 v128, v133
	v_mov_b32_e32 v130, v134
	s_add_i32 m0, s41, 0xc000
	ds_read_b128 v[174:177], v140
	ds_read_b128 v[178:181], v140 offset:1024
	ds_read_b128 v[182:185], v140 offset:2048
	ds_read_b128 v[186:189], v140 offset:3072
	ds_read_b128 v[190:193], v140 offset:4096
	ds_read_b128 v[194:197], v140 offset:5120
	ds_read_b128 v[198:201], v140 offset:6144
	ds_read_b128 v[202:205], v140 offset:7168
	s_nop 0
	global_load_lds_dwordx4 v128, s[30:31]
	s_add_i32 m0, s41, 0xe000
	s_nop 0
	global_load_lds_dwordx4 v130, s[30:31]
	s_and_b64 vcc, exec, s[14:15]
	s_cbranch_vccnz .Lmy_lw_17
	s_cmp_lg_u32 s101, 0
	s_cbranch_scc1 .Lmy_rx_9
	s_waitcnt vmcnt(8)
	s_branch .Lmy_ry_9

.Lmy_ry_10:
	s_barrier
	s_add_i32 s55, s50, s3
	v_mov_b32_e32 v128, v135
	v_mov_b32_e32 v130, v136
	s_mov_b32 m0, s55
	s_nop 0
	ds_read_b128 v[64:67], v140 offset:16384
	ds_read_b128 v[68:71], v140 offset:17408
	ds_read_b128 v[72:75], v140 offset:18432
	ds_read_b128 v[76:79], v140 offset:19456
	ds_read_b128 v[80:83], v140 offset:20480
	ds_read_b128 v[84:87], v140 offset:21504
	ds_read_b128 v[88:91], v140 offset:22528
	ds_read_b128 v[92:95], v140 offset:23552
	v_mov_b32_e32 v131, v129
	global_load_lds_dwordx4 v128, s[36:37]
	s_add_i32 m0, s55, 0x2000
	v_mov_b32_e32 v128, v135
	global_load_lds_dwordx4 v130, s[36:37]
	v_mov_b32_e32 v130, v136
	s_add_i32 s55, s51, s3
	v_lshl_add_u64 v[190:191], s[36:37], 0, v[128:129]
	v_lshl_add_u64 v[190:191], v[190:191], 0, s[8:9]
	s_mov_b32 m0, s55
	v_lshl_add_u64 v[130:131], s[36:37], 0, v[130:131]
	global_load_lds_dwordx4 v[190:191], off
	v_lshl_add_u64 v[130:131], v[130:131], 0, s[8:9]
	s_add_i32 m0, s55, 0x2000
	v_mov_b32_e32 v128, v133
	global_load_lds_dwordx4 v[130:131], off
	v_mov_b32_e32 v130, v134
	s_mov_b32 m0, s41
	s_nop 0
	global_load_lds_dwordx4 v128, s[34:35]
	s_mov_b32 m0, s42
	s_nop 0
	global_load_lds_dwordx4 v130, s[34:35]
	s_and_b64 vcc, exec, s[14:15]
	s_cbranch_vccnz .Lmy_lw_18
	s_cmp_lg_u32 s101, 0
	s_cbranch_scc1 .Lmy_rx_11
	s_waitcnt vmcnt(8)
	s_branch .Lmy_ry_11

.Lmy_ry_12:
	s_mov_b32 s101, 0
	s_barrier
	s_add_i32 s55, 0, 0x18000
	s_nop 2
	v_add_u32_e32 v8, s55, v137
	s_add_i32 s63, 0, 0x1c000
	ds_read_b128 v[0:3], v8
	ds_read_b128 v[4:7], v8 offset:1024
	ds_read_b128 v[142:145], v8 offset:2048
	ds_read_b128 v[146:149], v8 offset:3072
	v_add_u32_e32 v8, s63, v137
	ds_read_b128 v[150:153], v8
	ds_read_b128 v[154:157], v8 offset:1024
	ds_read_b128 v[158:161], v8 offset:2048
	ds_read_b128 v[162:165], v8 offset:3072
	s_add_u32 s64, s34, 0x40000
	v_mov_b32_e32 v64, v133
	v_mov_b32_e32 v65, v134
	s_addc_u32 s65, s35, 0
	s_mov_b32 m0, s43
	ds_read_b128 v[8:11], v140 offset:32768
	ds_read_b128 v[12:15], v140 offset:33792
	ds_read_b128 v[16:19], v140 offset:34816
	ds_read_b128 v[20:23], v140 offset:35840
	ds_read_b128 v[24:27], v140 offset:36864
	ds_read_b128 v[28:31], v140 offset:37888
	ds_read_b128 v[32:35], v140 offset:38912
	ds_read_b128 v[36:39], v140 offset:39936
	s_nop 0
	global_load_lds_dwordx4 v64, s[64:65]
	s_mov_b32 m0, s44
	s_nop 0
	global_load_lds_dwordx4 v65, s[64:65]
	s_and_b64 vcc, exec, s[14:15]
	s_cbranch_vccnz .Lmy_lw_19
	s_waitcnt vmcnt(8)

.LBB0_2954:
	s_mov_b32 s101, 0
	s_cmp_lt_i32 s56, 19
	s_cselect_b64 s[6:7], -1, 0
	s_and_b64 s[6:7], s[6:7], s[8:9]
	s_andn2_b64 vcc, exec, s[6:7]
	s_cbranch_vccnz .LBB0_2971
	s_waitcnt vmcnt(0)
	v_mbcnt_hi_u32_b32 v134, -1, v254
	v_mov_b32_e32 v0, v134
	s_cmpk_gt_i32 s92, 0x2ff
	s_cbranch_scc1 .LBB0_2971
	s_lshl_b32 s3, s33, 10
	v_lshl_add_u32 v1, v0, 4, s3
	v_add_u32_e32 v2, 0x2000, v1
	v_ashrrev_i32_e32 v3, 31, v2
	v_lshrrev_b32_e32 v3, 22, v3
	v_add_u32_e32 v3, v2, v3
	v_ashrrev_i32_e32 v3, 10, v3
	v_mul_i32_i24_e32 v5, 0x400, v3
	v_sub_u32_e32 v2, v2, v5
	v_lshrrev_b32_e32 v5, 4, v2
	v_bitop3_b32 v2, v5, v2, 32 bitop3:0x6c
	v_ashrrev_i32_e32 v5, 31, v2
	v_lshrrev_b32_e32 v5, 26, v5
	v_add_u32_e32 v5, v2, v5
	v_ashrrev_i32_e32 v6, 6, v5
	v_and_b32_e32 v5, 0xffc0, v5
	v_sub_u32_e32 v2, v2, v5
	v_lshrrev_b16_e32 v5, 7, v2
	v_lshlrev_b32_e32 v4, 5, v3
	v_and_b32_e32 v5, 1, v5
	v_lshlrev_b32_e32 v3, 3, v3
	v_add_u16_e32 v2, v2, v5
	v_mov_b32_e32 v5, 1
	v_and_b32_e32 v3, -16, v3
	v_and_b32_e32 v4, 32, v4
	v_ashrrev_i16_sdwa v2, v5, sext(v2) dst_sel:DWORD dst_unused:UNUSED_PAD src0_sel:DWORD src1_sel:BYTE_0
	v_add_u32_e32 v3, v6, v3
	v_add_u32_sdwa v2, v4, sext(v2) dst_sel:DWORD dst_unused:UNUSED_PAD src0_sel:DWORD src1_sel:WORD_0
	v_and_b32_e32 v4, 3, v6
	s_mov_b32 s8, 0xfffffe0
	v_lshrrev_b32_e32 v6, 2, v3
	v_lshlrev_b32_e32 v7, 1, v3
	v_and_or_b32 v4, v3, s8, v4
	v_and_b32_e32 v6, 4, v6
	v_and_b32_e32 v7, 24, v7
	v_or3_b32 v4, v4, v6, v7
	v_ashrrev_i32_e32 v6, 31, v1
	v_lshrrev_b32_e32 v6, 22, v6
	v_add_u32_e32 v6, v1, v6
	v_ashrrev_i32_e32 v6, 10, v6
	v_mul_i32_i24_e32 v8, 0x400, v6
	v_sub_u32_e32 v1, v1, v8
	v_lshrrev_b32_e32 v8, 4, v1
	v_bitop3_b32 v1, v8, v1, 32 bitop3:0x6c
	v_ashrrev_i32_e32 v8, 31, v1
	v_lshrrev_b32_e32 v8, 26, v8
	v_add_u32_e32 v8, v1, v8
	v_ashrrev_i32_e32 v9, 6, v8
	v_and_b32_e32 v8, 0xc0, v8
	v_sub_u32_e32 v1, v1, v8
	v_ashrrev_i16_sdwa v1, v5, sext(v1) dst_sel:DWORD dst_unused:UNUSED_PAD src0_sel:DWORD src1_sel:BYTE_0
	v_lshlrev_b32_e32 v5, 3, v6
	v_and_b32_e32 v5, -16, v5
	v_lshlrev_b32_e32 v7, 5, v6
	v_add_u32_e32 v5, v9, v5
	v_and_b32_e32 v6, 3, v9
	v_and_or_b32 v6, v5, s8, v6
	s_mul_hi_i32 s8, s92, 0x2aaaaaab
	s_lshr_b32 s9, s8, 31
	s_ashr_i32 s8, s8, 3
	s_add_i32 s8, s8, s9
	s_mul_i32 s9, s8, 48
	s_sub_i32 s9, s92, s9
	s_mul_i32 s10, s9, 43
	s_bfe_u32 s11, s10, 0x1000f
	s_bfe_u32 s10, s10, 0x80008
	s_add_i32 s14, s10, s11
	s_load_dwordx2 s[16:17], s[0:1], 0xf0
	s_mul_i32 s11, s14, 6
	s_sub_i32 s9, s9, s11
	s_mul_i32 s10, s8, 6
	s_sext_i32_i8 s9, s9
	s_lshr_b32 s12, s90, 8
	s_add_i32 s26, s10, s9
	s_waitcnt lgkmcnt(0)
	s_add_u32 s36, s16, 0x62358000
	s_addc_u32 s37, s17, 0
	s_ashr_i32 s27, s26, 31
	s_lshl_b64 s[10:11], s[26:27], 19
	s_add_u32 s28, s36, s10
	s_addc_u32 s29, s37, s11
	s_add_u32 s38, s16, 0x233d8000
	s_addc_u32 s39, s17, 0
	s_ashr_i32 s9, s8, 31
	s_bfe_i64 s[10:11], s[14:15], 0x80000
	v_and_b32_e32 v7, 32, v7
	s_lshl_b64 s[8:9], s[8:9], 22
	s_lshl_b64 s[10:11], s[10:11], 12
	v_add_u32_sdwa v1, v7, sext(v1) dst_sel:DWORD dst_unused:UNUSED_PAD src0_sel:DWORD src1_sel:WORD_0
	v_lshrrev_b32_e32 v7, 2, v5
	v_lshlrev_b32_e32 v8, 1, v5
	s_add_u32 s8, s38, s8
	v_lshlrev_b32_e32 v5, 11, v5
	v_and_b32_e32 v7, 4, v7
	v_and_b32_e32 v8, 24, v8
	s_addc_u32 s9, s39, s9
	v_lshl_add_u32 v135, v1, 1, v5
	v_lshlrev_b32_e32 v1, 12, v1
	v_or3_b32 v6, v6, v7, v8
	s_add_u32 s8, s8, s10
	v_and_b32_e32 v1, 0xffff8000, v1
	s_addc_u32 s9, s9, s11
	v_lshl_add_u32 v137, v6, 4, v1
	v_lshlrev_b32_e32 v1, 12, v2
	s_add_u32 s30, s8, 0x4000000
	v_and_b32_e32 v1, 0xffff8000, v1
	s_addc_u32 s31, s9, 0
	v_lshlrev_b32_e32 v3, 11, v3
	v_lshl_add_u32 v138, v4, 4, v1
	s_add_i32 s40, s3, 0
	v_lshl_add_u32 v136, v2, 1, v3
	v_mov_b32_e32 v1, v137
	v_mov_b32_e32 v2, v138
	s_add_i32 m0, s40, 0x10000
	v_mov_b32_e32 v128, v137
	global_load_lds_dwordx4 v1, s[30:31]
	s_add_i32 m0, s40, 0x12000
	v_mov_b32_e32 v129, 0
	global_load_lds_dwordx4 v2, s[30:31]
	v_mov_b32_e32 v2, v138
	s_mov_b64 s[8:9], 0x800
	v_lshl_add_u64 v[4:5], s[30:31], 0, v[128:129]
	v_mov_b32_e32 v3, v129
	v_lshl_add_u64 v[4:5], v[4:5], 0, s[8:9]
	s_add_i32 m0, s40, 0x14000
	v_lshl_add_u64 v[2:3], s[30:31], 0, v[2:3]
	global_load_lds_dwordx4 v[4:5], off
	v_lshl_add_u64 v[2:3], v[2:3], 0, s[8:9]
	s_add_i32 m0, s40, 0x16000
	s_add_i32 s41, s40, 0x2000
	global_load_lds_dwordx4 v[2:3], off
	v_mov_b32_e32 v1, v136
	v_mov_b32_e32 v2, v135
	s_mov_b32 m0, s40
	s_add_u32 s10, s28, 0x40000
	s_addc_u32 s11, s29, 0
	global_load_lds_dwordx4 v2, s[28:29]
	s_mov_b32 m0, s41
	s_add_i32 s42, s40, 0x4000
	global_load_lds_dwordx4 v1, s[28:29]
	v_mov_b32_e32 v1, v135
	v_mov_b32_e32 v2, v136
	s_mov_b32 m0, s42
	s_add_i32 s43, s40, 0x6000
	s_cmp_eq_u32 s12, 1
	global_load_lds_dwordx4 v1, s[10:11]
	s_mov_b32 m0, s43
	s_nop 0
	global_load_lds_dwordx4 v2, s[10:11]
	s_cselect_b64 s[10:11], -1, 0
	s_cmp_lg_u32 s12, 1
	s_cbranch_scc1 .LBB0_2958
	s_barrier

.LBB0_2964:
	ds_read_b128 v[144:147], v140
	ds_read_b128 v[148:151], v140 offset:1024
	ds_read_b128 v[152:155], v140 offset:2048
	ds_read_b128 v[156:159], v140 offset:3072
	ds_read_b128 v[160:163], v141
	ds_read_b128 v[164:167], v141 offset:1024
	ds_read_b128 v[168:171], v141 offset:2048
	ds_read_b128 v[172:175], v141 offset:3072
	s_add_u32 s30, s28, 0xfffc0080
	s_addc_u32 s31, s29, -1
	s_cmp_eq_u32 s53, 12
	s_cselect_b32 s31, s21, s31
	s_cselect_b32 s30, s20, s30
	s_cselect_b32 s35, s23, s52
	s_cselect_b32 s34, s22, s19
	v_mov_b32_e32 v128, v135
	v_mov_b32_e32 v130, v136
	s_add_i32 m0, s40, 0xc000
	ds_read_b128 v[176:179], v142
	ds_read_b128 v[180:183], v142 offset:1024
	ds_read_b128 v[184:187], v142 offset:2048
	ds_read_b128 v[188:191], v142 offset:3072
	ds_read_b128 v[192:195], v142 offset:4096
	ds_read_b128 v[196:199], v142 offset:5120
	ds_read_b128 v[200:203], v142 offset:6144
	ds_read_b128 v[204:207], v142 offset:7168
	s_nop 0
	global_load_lds_dwordx4 v128, s[28:29]
	s_add_i32 m0, s40, 0xe000
	s_nop 0
	global_load_lds_dwordx4 v130, s[28:29]
	s_and_b64 vcc, exec, s[14:15]
	s_cbranch_vccnz .Lmy_lw_21
	s_cmp_lg_u32 s101, 0
	s_cbranch_scc1 .Lmy_rx_13
	s_waitcnt vmcnt(8)
	s_branch .Lmy_ry_13

.Lmy_ry_14:
	s_barrier
	s_add_i32 s54, s49, s3
	v_mov_b32_e32 v128, v137
	v_mov_b32_e32 v196, v138
	s_mov_b32 m0, s54
	s_nop 0
	ds_read_b128 v[64:67], v142 offset:16384
	ds_read_b128 v[68:71], v142 offset:17408
	ds_read_b128 v[72:75], v142 offset:18432
	ds_read_b128 v[76:79], v142 offset:19456
	ds_read_b128 v[80:83], v142 offset:20480
	ds_read_b128 v[84:87], v142 offset:21504
	ds_read_b128 v[88:91], v142 offset:22528
	ds_read_b128 v[92:95], v142 offset:23552
	v_mov_b32_e32 v197, v129
	global_load_lds_dwordx4 v128, s[34:35]
	s_add_i32 m0, s54, 0x2000
	v_mov_b32_e32 v128, v137
	global_load_lds_dwordx4 v196, s[34:35]
	v_mov_b32_e32 v196, v138
	s_add_i32 s54, s50, s3
	v_lshl_add_u64 v[198:199], s[34:35], 0, v[128:129]
	v_lshl_add_u64 v[198:199], v[198:199], 0, s[8:9]
	s_mov_b32 m0, s54
	v_lshl_add_u64 v[196:197], s[34:35], 0, v[196:197]
	global_load_lds_dwordx4 v[198:199], off
	v_lshl_add_u64 v[196:197], v[196:197], 0, s[8:9]
	s_add_i32 m0, s54, 0x2000
	v_mov_b32_e32 v128, v135
	global_load_lds_dwordx4 v[196:197], off
	v_mov_b32_e32 v196, v136
	s_mov_b32 m0, s40
	s_nop 0
	global_load_lds_dwordx4 v128, s[30:31]
	s_mov_b32 m0, s41
	s_nop 0
	global_load_lds_dwordx4 v196, s[30:31]
	s_and_b64 vcc, exec, s[14:15]
	s_cbranch_vccnz .Lmy_lw_22
	s_cmp_lg_u32 s101, 0
	s_cbranch_scc1 .Lmy_rx_15
	s_waitcnt vmcnt(8)
	s_branch .Lmy_ry_15

.Lmy_ry_16:
	s_mov_b32 s101, 0
	s_barrier
	s_add_i32 s63, 0, 0x18000
	s_add_i32 s64, 0, 0x1c000
	s_nop 0
	v_add_u32_e32 v12, s63, v139
	v_add_u32_e32 v16, s64, v139
	ds_read_b128 v[0:3], v12
	ds_read_b128 v[4:7], v12 offset:1024
	ds_read_b128 v[8:11], v12 offset:2048
	ds_read_b128 v[12:15], v12 offset:3072
	ds_read_b128 v[144:147], v16
	ds_read_b128 v[148:151], v16 offset:1024
	ds_read_b128 v[152:155], v16 offset:2048
	ds_read_b128 v[156:159], v16 offset:3072
	s_add_u32 s54, s30, 0x40000
	v_mov_b32_e32 v64, v135
	v_mov_b32_e32 v65, v136
	s_addc_u32 s55, s31, 0
	s_mov_b32 m0, s42
	ds_read_b128 v[16:19], v142 offset:32768
	ds_read_b128 v[20:23], v142 offset:33792
	ds_read_b128 v[24:27], v142 offset:34816
	ds_read_b128 v[28:31], v142 offset:35840
	ds_read_b128 v[32:35], v142 offset:36864
	ds_read_b128 v[36:39], v142 offset:37888
	ds_read_b128 v[40:43], v142 offset:38912
	ds_read_b128 v[44:47], v142 offset:39936
	s_nop 0
	global_load_lds_dwordx4 v64, s[54:55]
	s_mov_b32 m0, s43
	s_nop 0
	global_load_lds_dwordx4 v65, s[54:55]
	s_and_b64 vcc, exec, s[14:15]
	s_cbranch_vccnz .Lmy_lw_23
	s_waitcnt vmcnt(8)
